# static s_setprio 1 for the trailing wave half (waves 4-7) set once at kernel entry; all per-phase priority flips removed from the four GEMM K-loops
# speedup vs baseline: 1.0067x; 1.0067x over previous
; #define LAS __attribute__((address_space(3)))
; __global__ void __launch_bounds__(NTHR, 2) hybrid_fwd(Args args) {
;     ...
;     const int wave = __builtin_amdgcn_readfirstlane((int)threadIdx.x >> 6);
;     const int G = gridDim.x, bx = blockIdx.x;
;     const int gw = bx * NWAVES + wave, NGW = G * NWAVES;
;     ...
;     unsigned char* ws = args.ws;
;     const float* x = args.in[0]; const float* ln1 = args.in[1]; const float* w_in = args.in[2];
;     const float* lq1 = args.in[3]; const float* lk1 = args.in[4]; const float* lq2 = args.in[5]; const float* lk2 = args.in[6];
;     const float* g_diff = args.in[7]; const float* g_sb = args.in[8]; const float* w_out = args.in[9]; const float* ln2 = args.in[10];
;     const float* w1 = args.in[11]; const float* w2 = args.in[12]; const float* ln_f = args.in[13];
;     float* out = args.out;
;     bf16* Win_t = (bf16*)(ws + WS_WIN); bf16* Wout_t = (bf16*)(ws + WS_WOUT); unsigned char* W1_8t = ws + WS_W1; unsigned char* W2_8t = ws + WS_W2; unsigned char* Hb8 = ws + WS_H8;
;     float* cs = (float*)(ws + WS_CS); float* ss1 = (float*)(ws + WS_SS1); float* ss2 = (float*)(ws + WS_SS2);
;     bf16* Hb = (bf16*)(ws + WS_H); bf16* QKV = (bf16*)(ws + WS_QKV); bf16* MIX = (bf16*)(ws + WS_MIX); unsigned char* U8 = ws + WS_U;
;     const int lo = args.ph_lo, hi_ph = args.ph_hi;
;     ...
;     unsigned* ctl = (unsigned*)(ws + WS_CTL);
;     const bool t0 = (wave == 0) && (__builtin_amdgcn_mbcnt_hi(~0u, __builtin_amdgcn_mbcnt_lo(~0u, 0u)) == 0);
;     if (args.ph_lo < 0) grid.sync();
;     volatile LAS unsigned* bst = (volatile LAS unsigned*)(lds + RING_BYTES);
;     if (t0) { bst[0] = 0u; bst[1] = 0u; }
;     __syncthreads();
;     XcdBarrier xbar = xcd_barrier_post(ctl + 1024, bst, t0);
;     ...
;     if (IN(0)) {
;         FRESH_IDS;
;         LAS float* scr = (LAS float*)(lds + wave * 16384);
;         constexpr int I_IN = (DM / 64) * (PW / 32), I_OUT = (DM / 64) * (DM / 32), I_1 = (DM / 64) * (FF / 32), I_2 = (FF / 64) * (DM / 32);
;         constexpr int NITEMS = I_IN + I_OUT + I_1 + I_2;
;         for (int it = gw; it < NITEMS; it += NGW) {
;             int r = it;
.LBB0_7:
	s_or_b64 exec, exec, s[4:5]
	s_lshr_b32 s74, s3, 6
	s_cmp_lt_u32 s74, 4
	s_cbranch_scc1 .Lhy_prio_skip
	s_setprio 1
.Lhy_prio_skip:
	s_lshl_b32 s4, s2, 3
	s_add_i32 s68, s74, s4
	s_lshl_b32 s70, s76, 3
	s_add_u32 s84, s50, 0x1800000
	s_addc_u32 s85, s51, 0
	s_add_u32 s82, s50, 0x2000000
	s_addc_u32 s83, s51, 0
	s_add_u32 s80, s50, 0x4000000
	s_addc_u32 s81, s51, 0
	s_add_u32 s8, s50, 0x6000000
	s_addc_u32 s9, s51, 0
	s_cmp_lt_i32 s72, 1
	s_cselect_b64 s[4:5], -1, 0
	s_cmp_gt_i32 s73, 0
	s_cselect_b64 s[6:7], -1, 0
	s_and_b64 s[6:7], s[4:5], s[6:7]
	s_andn2_b64 vcc, exec, s[6:7]
	s_cbranch_vccnz .LBB0_61
	v_mbcnt_lo_u32_b32 v0, -1, 0
	v_mbcnt_hi_u32_b32 v53, -1, v0
	v_mov_b32_e32 v48, v53
	s_mov_b32 s11, 0
	s_cmpk_gt_i32 s68, 0x5fff
	v_and_b32_e32 v64, 7, v48
	s_cbranch_scc1 .LBB0_51
	s_lshl_b32 s4, s74, 14
	s_add_i32 s4, s4, 0
	v_ashrrev_i32_e32 v49, 3, v48
	v_lshlrev_b32_e32 v0, 4, v64
	s_movk_i32 s5, 0x84
	v_mov_b32_e32 v1, 0
	v_add_u32_e32 v4, s4, v0
	v_mul_lo_u32 v5, v49, s5
	v_mul_u32_u24_e32 v6, 0x420, v64
	v_lshlrev_b32_e32 v7, 2, v49
	v_lshlrev_b32_e32 v2, 3, v64
	v_mov_b32_e32 v3, v1
	v_add3_u32 v61, s4, v6, v7
	s_cmp_lg_u64 s[40:41], 0
	v_add_u32_e32 v6, 0x1080, v5
	v_add_u32_e32 v62, v4, v5
	v_lshl_add_u64 v[32:33], s[44:45], 0, v[0:1]
	v_add_u32_e32 v58, 8, v49
	v_add_u32_e32 v59, 16, v49
	v_add_u32_e32 v60, 24, v49
	v_lshl_add_u64 v[34:35], s[80:81], 0, v[2:3]
	v_lshl_add_u64 v[36:37], s[42:43], 0, v[0:1]
	s_cselect_b64 s[12:13], -1, 0
	v_lshl_add_u64 v[38:39], s[82:83], 0, v[2:3]
	v_lshl_add_u64 v[40:41], s[38:39], 0, v[0:1]
	v_lshl_add_u64 v[42:43], s[84:85], 0, v[0:1]
	v_lshl_add_u64 v[44:45], s[56:57], 0, v[0:1]
	v_lshl_add_u64 v[46:47], s[50:51], 0, v[0:1]
	s_lshl_b32 s15, s68, 5
	s_lshl_b32 s17, s70, 5
	s_brev_b32 s14, 34
	v_add_u32_e32 v63, 0x420, v62
	v_add_u32_e32 v65, 0x428, v62
	v_add_u32_e32 v66, 0x840, v62
	v_add_u32_e32 v67, 0x848, v62
	v_add_u32_e32 v68, 0xc60, v62
	v_add_u32_e32 v69, 0xc68, v62
	v_add_u32_e32 v70, 0x1080, v62
	v_add_u32_e32 v71, 0x1088, v62
	v_add_u32_e32 v72, 0x14a0, v62
	v_add_u32_e32 v73, 0x14a8, v62
	v_add_u32_e32 v74, 0x18c0, v62
	v_add_u32_e32 v75, 0x18c8, v62
	v_add_u32_e32 v76, 0x1ce0, v62
	v_add_u32_e32 v77, 0x1ce8, v62
	s_mov_b32 s16, 0x42000000
	s_movk_i32 s22, 0x7fff
	s_mov_b32 s23, 0xffff0000
	s_movk_i32 s24, 0x6000
	v_add_u32_e32 v78, v4, v6
	s_mov_b32 s25, s68
	s_branch .LBB0_11

; #define PG8_STAGE(bufoff, gbase, voff) do { _Pragma("unroll") for (int _i = 0; _i < 2; ++_i) \
;         __builtin_amdgcn_global_load_lds((const unsigned*)((const char*)(gbase) + (voff)[_i]), (PG8_LAS unsigned*)(lds + (bufoff) + ldsw + _i * 8192), 16, 0, 0); } while (0)
; #define PG8_LDA(dst, b, h) do { _Pragma("unroll") for (int m = 0; m < 4; ++m) { if constexpr (FP8) dst##8[m] = PG8_LD32(lds + PG8_SA(b, h) + aoff + m * 2048); else { _Pragma("unroll") for (int k = 0; k < 2; ++k) dst[m][k] = *(const PG8_LAS bf16x8*)(lds + PG8_SA(b, h) + aoff + m * 2048 + k * 1024); } } } while (0)
; #define PG8_LDB(dst, b, h) do { _Pragma("unroll") for (int n = 0; n < 2; ++n) { if constexpr (FP8) dst##8[n] = PG8_LD32(lds + PG8_SB(b, h) + boff + n * 2048); else { _Pragma("unroll") for (int k = 0; k < 2; ++k) dst[n][k] = *(const PG8_LAS bf16x8*)(lds + PG8_SB(b, h) + boff + n * 2048 + k * 1024); } } } while (0)
; #define PG8_WAIT_V(n) asm volatile("s_waitcnt vmcnt(" #n ")" ::: "memory")
; #define PG8_WAIT_L(n) asm volatile("s_waitcnt lgkmcnt(" #n ")" ::: "memory")
; #define PG8_BAR __builtin_amdgcn_s_barrier()
; #define PG8_SCHED __builtin_amdgcn_sched_barrier(0)
; template <class Epi, class Sched, bool ALIGN_EPI = false, bool SP2 = false, bool FP8 = false>
; __device__ __forceinline__ void gemm_phase(PG8_LAS unsigned char* lds, const Gemm g, const Sched& S, const Epi& E, int wave_id) {
;     ...
;             PG8_LDB(B0, 0, 0); PG8_LDB(B1, 0, 1); PG8_SCHED; PG8_LDA(At, 0, 0); PG8_STAGE(PG8_SA(1, 1), a1 + hstep, voffA);
;             PG8_WAIT_V(8); PG8_WAIT_L(0); PG8_BAR; PG8_MMA(0, 0, At, B0); PG8_MMA(0, 1, At, B1); PG8_BAR; PG8_SCHED;
;             PG8_LDA(At, 0, 1); PG8_STAGE(PG8_SB(0, 0), b2, voffB); PG8_STAGE(PG8_SB(0, 1), b2 + hstep, voffB); PG8_STAGE(PG8_SA(0, 0), a2, voffA);
;             PG8_WAIT_V(8); PG8_WAIT_L(0); PG8_BAR; PG8_MMA(1, 0, At, B0); PG8_MMA(1, 1, At, B1); PG8_BAR; PG8_SCHED;
.LBB0_125:
	ds_read_b128 v[128:131], v186
	ds_read_b128 v[132:135], v186 offset:1024
	ds_read_b128 v[136:139], v186 offset:2048
	ds_read_b128 v[156:159], v186 offset:3072
	ds_read_b128 v[160:163], v187
	ds_read_b128 v[164:167], v187 offset:1024
	ds_read_b128 v[168:171], v187 offset:2048
	ds_read_b128 v[172:175], v187 offset:3072
	s_add_u32 s34, s30, 0xfff80080
	s_addc_u32 s35, s31, -1
	s_cmp_eq_u32 s95, 28
	s_cselect_b32 s43, s23, s35
	s_cselect_b32 s42, s91, s34
	s_cselect_b32 s35, s21, s94
	s_cselect_b32 s34, s92, s93
	v_lshl_add_u64 v[180:181], s[30:31], 0, v[148:149]
	s_add_i32 m0, s55, 0xc000
	ds_read_b128 v[176:179], v188
	ds_read_b128 v[192:195], v188 offset:1024
	ds_read_b128 v[196:199], v188 offset:2048
	ds_read_b128 v[200:203], v188 offset:3072
	ds_read_b128 v[204:207], v188 offset:4096
	ds_read_b128 v[208:211], v188 offset:5120
	ds_read_b128 v[212:215], v188 offset:6144
	ds_read_b128 v[216:219], v188 offset:7168
	global_load_lds_dwordx4 v[180:181], off
	v_lshl_add_u64 v[180:181], s[30:31], 0, v[150:151]
	s_add_i32 m0, s55, 0xe000
	s_nop 0
	global_load_lds_dwordx4 v[180:181], off
	s_waitcnt vmcnt(8)
	s_waitcnt lgkmcnt(0)
	s_barrier
	s_waitcnt lgkmcnt(0)
	v_mfma_f32_16x16x32_bf16 v[124:127], v[128:131], v[176:179], v[124:127]
	v_mfma_f32_16x16x32_bf16 v[120:123], v[136:139], v[176:179], v[120:123]
	v_mfma_f32_16x16x32_bf16 v[108:111], v[128:131], v[196:199], v[108:111]
	v_mfma_f32_16x16x32_bf16 v[104:107], v[136:139], v[196:199], v[104:107]
	v_mfma_f32_16x16x32_bf16 v[92:95], v[128:131], v[204:207], v[92:95]
	v_mfma_f32_16x16x32_bf16 v[88:91], v[136:139], v[204:207], v[88:91]
	v_mfma_f32_16x16x32_bf16 v[76:79], v[128:131], v[212:215], v[76:79]
	v_mfma_f32_16x16x32_bf16 v[72:75], v[136:139], v[212:215], v[72:75]
	v_mfma_f32_16x16x32_bf16 v[124:127], v[132:135], v[192:195], v[124:127]
	v_mfma_f32_16x16x32_bf16 v[120:123], v[156:159], v[192:195], v[120:123]
	v_mfma_f32_16x16x32_bf16 v[108:111], v[132:135], v[200:203], v[108:111]
	v_mfma_f32_16x16x32_bf16 v[104:107], v[156:159], v[200:203], v[104:107]
	v_mfma_f32_16x16x32_bf16 v[92:95], v[132:135], v[208:211], v[92:95]
	v_mfma_f32_16x16x32_bf16 v[88:91], v[156:159], v[208:211], v[88:91]
	v_mfma_f32_16x16x32_bf16 v[76:79], v[132:135], v[216:219], v[76:79]
	v_mfma_f32_16x16x32_bf16 v[72:75], v[156:159], v[216:219], v[72:75]
	v_mfma_f32_16x16x32_bf16 v[116:119], v[160:163], v[176:179], v[116:119]
	v_mfma_f32_16x16x32_bf16 v[112:115], v[168:171], v[176:179], v[112:115]
	v_mfma_f32_16x16x32_bf16 v[100:103], v[160:163], v[196:199], v[100:103]
	v_mfma_f32_16x16x32_bf16 v[96:99], v[168:171], v[196:199], v[96:99]
	v_mfma_f32_16x16x32_bf16 v[84:87], v[160:163], v[204:207], v[84:87]
	v_mfma_f32_16x16x32_bf16 v[80:83], v[168:171], v[204:207], v[80:83]
	v_mfma_f32_16x16x32_bf16 v[68:71], v[160:163], v[212:215], v[68:71]
	v_mfma_f32_16x16x32_bf16 v[64:67], v[168:171], v[212:215], v[64:67]
	v_mfma_f32_16x16x32_bf16 v[116:119], v[164:167], v[192:195], v[116:119]
	v_mfma_f32_16x16x32_bf16 v[112:115], v[172:175], v[192:195], v[112:115]
	v_mfma_f32_16x16x32_bf16 v[100:103], v[164:167], v[200:203], v[100:103]
	v_mfma_f32_16x16x32_bf16 v[96:99], v[172:175], v[200:203], v[96:99]
	v_mfma_f32_16x16x32_bf16 v[84:87], v[164:167], v[208:211], v[84:87]
	v_mfma_f32_16x16x32_bf16 v[80:83], v[172:175], v[208:211], v[80:83]
	v_mfma_f32_16x16x32_bf16 v[68:71], v[164:167], v[216:219], v[68:71]
	v_mfma_f32_16x16x32_bf16 v[64:67], v[172:175], v[216:219], v[64:67]
	s_barrier
	s_add_i32 s78, s88, s44
	v_lshl_add_u64 v[180:181], s[34:35], 0, v[144:145]
	s_mov_b32 m0, s78
	ds_read_b128 v[176:179], v188 offset:16384
	ds_read_b128 v[192:195], v188 offset:17408
	ds_read_b128 v[196:199], v188 offset:18432
	ds_read_b128 v[200:203], v188 offset:19456
	ds_read_b128 v[204:207], v188 offset:20480
	ds_read_b128 v[208:211], v188 offset:21504
	ds_read_b128 v[212:215], v188 offset:22528
	ds_read_b128 v[216:219], v188 offset:23552
	global_load_lds_dwordx4 v[180:181], off
	s_add_i32 m0, s78, 0x2000
	s_add_u32 s96, s34, 0x80000
	v_lshl_add_u64 v[220:221], s[34:35], 0, v[140:141]
	s_addc_u32 s97, s35, 0
	s_add_i32 s78, s89, s44
	global_load_lds_dwordx4 v[220:221], off
	v_lshl_add_u64 v[222:223], s[96:97], 0, v[144:145]
	s_mov_b32 m0, s78
	v_lshl_add_u64 v[224:225], s[42:43], 0, v[142:143]
	global_load_lds_dwordx4 v[222:223], off
	v_lshl_add_u64 v[222:223], s[96:97], 0, v[140:141]
	s_add_i32 m0, s78, 0x2000
	s_nop 0
	global_load_lds_dwordx4 v[222:223], off
	v_lshl_add_u64 v[222:223], s[42:43], 0, v[146:147]
	s_mov_b32 m0, s55
	s_nop 0
	global_load_lds_dwordx4 v[222:223], off
	s_mov_b32 m0, s56
	s_nop 0
	global_load_lds_dwordx4 v[224:225], off
	s_waitcnt vmcnt(8)
	s_waitcnt lgkmcnt(0)
	s_barrier
; #define PG8_STAGE(bufoff, gbase, voff) do { _Pragma("unroll") for (int _i = 0; _i < 2; ++_i) \
;         __builtin_amdgcn_global_load_lds((const unsigned*)((const char*)(gbase) + (voff)[_i]), (PG8_LAS unsigned*)(lds + (bufoff) + ldsw + _i * 8192), 16, 0, 0); } while (0)
; #define PG8_LDA(dst, b, h) do { _Pragma("unroll") for (int m = 0; m < 4; ++m) { if constexpr (FP8) dst##8[m] = PG8_LD32(lds + PG8_SA(b, h) + aoff + m * 2048); else { _Pragma("unroll") for (int k = 0; k < 2; ++k) dst[m][k] = *(const PG8_LAS bf16x8*)(lds + PG8_SA(b, h) + aoff + m * 2048 + k * 1024); } } } while (0)
; #define PG8_LDB(dst, b, h) do { _Pragma("unroll") for (int n = 0; n < 2; ++n) { if constexpr (FP8) dst##8[n] = PG8_LD32(lds + PG8_SB(b, h) + boff + n * 2048); else { _Pragma("unroll") for (int k = 0; k < 2; ++k) dst[n][k] = *(const PG8_LAS bf16x8*)(lds + PG8_SB(b, h) + boff + n * 2048 + k * 1024); } } } while (0)
; #define PG8_WAIT_V(n) asm volatile("s_waitcnt vmcnt(" #n ")" ::: "memory")
; #define PG8_WAIT_L(n) asm volatile("s_waitcnt lgkmcnt(" #n ")" ::: "memory")
; #define PG8_BAR __builtin_amdgcn_s_barrier()
; #define PG8_SCHED __builtin_amdgcn_sched_barrier(0)
; template <class Epi, class Sched, bool ALIGN_EPI = false, bool SP2 = false, bool FP8 = false>
; __device__ __forceinline__ void gemm_phase(PG8_LAS unsigned char* lds, const Gemm g, const Sched& S, const Epi& E, int wave_id) {
;     ...
;             PG8_LDA(At, 0, 1); PG8_STAGE(PG8_SB(0, 0), b2, voffB); PG8_STAGE(PG8_SB(0, 1), b2 + hstep, voffB); PG8_STAGE(PG8_SA(0, 0), a2, voffA);
;             PG8_WAIT_V(8); PG8_WAIT_L(0); PG8_BAR; PG8_MMA(1, 0, At, B0); PG8_MMA(1, 1, At, B1); PG8_BAR; PG8_SCHED;
;             PG8_LDB(B0, 1, 0); PG8_LDB(B1, 1, 1); PG8_SCHED; PG8_LDA(At, 1, 0); PG8_STAGE(PG8_SA(0, 1), a2 + hstep, voffA);
;             PG8_WAIT_V(8); PG8_WAIT_L(0); PG8_BAR; PG8_MMA(0, 0, At, B0); PG8_MMA(0, 1, At, B1); PG8_BAR; PG8_SCHED;
;             PG8_LDA(At, 1, 1); PG8_STAGE(PG8_SB(1, 0), b3, voffB); PG8_STAGE(PG8_SB(1, 1), b3 + hstep, voffB); PG8_STAGE(PG8_SA(1, 0), a3, voffA);
	s_waitcnt lgkmcnt(0)
	v_mfma_f32_16x16x32_bf16 v[60:63], v[128:131], v[176:179], v[60:63]
	v_mfma_f32_16x16x32_bf16 v[56:59], v[136:139], v[176:179], v[56:59]
	v_mfma_f32_16x16x32_bf16 v[44:47], v[128:131], v[196:199], v[44:47]
	v_mfma_f32_16x16x32_bf16 v[40:43], v[136:139], v[196:199], v[40:43]
	v_mfma_f32_16x16x32_bf16 v[28:31], v[128:131], v[204:207], v[28:31]
	v_mfma_f32_16x16x32_bf16 v[24:27], v[136:139], v[204:207], v[24:27]
	v_mfma_f32_16x16x32_bf16 v[12:15], v[128:131], v[212:215], v[12:15]
	v_mfma_f32_16x16x32_bf16 v[8:11], v[136:139], v[212:215], v[8:11]
	v_mfma_f32_16x16x32_bf16 v[60:63], v[132:135], v[192:195], v[60:63]
	v_mfma_f32_16x16x32_bf16 v[56:59], v[156:159], v[192:195], v[56:59]
	v_mfma_f32_16x16x32_bf16 v[44:47], v[132:135], v[200:203], v[44:47]
	v_mfma_f32_16x16x32_bf16 v[40:43], v[156:159], v[200:203], v[40:43]
	v_mfma_f32_16x16x32_bf16 v[28:31], v[132:135], v[208:211], v[28:31]
	v_mfma_f32_16x16x32_bf16 v[24:27], v[156:159], v[208:211], v[24:27]
	v_mfma_f32_16x16x32_bf16 v[12:15], v[132:135], v[216:219], v[12:15]
	v_mfma_f32_16x16x32_bf16 v[8:11], v[156:159], v[216:219], v[8:11]
	v_mfma_f32_16x16x32_bf16 v[52:55], v[160:163], v[176:179], v[52:55]
	v_mfma_f32_16x16x32_bf16 v[48:51], v[168:171], v[176:179], v[48:51]
	v_mfma_f32_16x16x32_bf16 v[36:39], v[160:163], v[196:199], v[36:39]
	v_mfma_f32_16x16x32_bf16 v[32:35], v[168:171], v[196:199], v[32:35]
	v_mfma_f32_16x16x32_bf16 v[20:23], v[160:163], v[204:207], v[20:23]
	v_mfma_f32_16x16x32_bf16 v[16:19], v[168:171], v[204:207], v[16:19]
	v_mfma_f32_16x16x32_bf16 v[4:7], v[160:163], v[212:215], v[4:7]
	v_mfma_f32_16x16x32_bf16 v[0:3], v[168:171], v[212:215], v[0:3]
	v_mfma_f32_16x16x32_bf16 v[52:55], v[164:167], v[192:195], v[52:55]
	v_mfma_f32_16x16x32_bf16 v[48:51], v[172:175], v[192:195], v[48:51]
	v_mfma_f32_16x16x32_bf16 v[36:39], v[164:167], v[200:203], v[36:39]
	v_mfma_f32_16x16x32_bf16 v[32:35], v[172:175], v[200:203], v[32:35]
	v_mfma_f32_16x16x32_bf16 v[20:23], v[164:167], v[208:211], v[20:23]
	v_mfma_f32_16x16x32_bf16 v[16:19], v[172:175], v[208:211], v[16:19]
	v_mfma_f32_16x16x32_bf16 v[4:7], v[164:167], v[216:219], v[4:7]
	v_mfma_f32_16x16x32_bf16 v[0:3], v[172:175], v[216:219], v[0:3]
	s_barrier
	s_add_i32 s78, 0, 0x18000
	s_add_i32 s79, 0, 0x1c000
	v_add_u32_e32 v156, s78, v183
	v_add_u32_e32 v172, s79, v183
	ds_read_b128 v[128:131], v156
	ds_read_b128 v[132:135], v156 offset:1024
	ds_read_b128 v[136:139], v156 offset:2048
	ds_read_b128 v[156:159], v156 offset:3072
	ds_read_b128 v[160:163], v172
	ds_read_b128 v[164:167], v172 offset:1024
	ds_read_b128 v[168:171], v172 offset:2048
	ds_read_b128 v[172:175], v172 offset:3072
	s_add_u32 s42, s42, 0x80000
	s_addc_u32 s43, s43, 0
	s_mov_b32 m0, s57
	v_lshl_add_u64 v[226:227], s[42:43], 0, v[146:147]
	ds_read_b128 v[176:179], v188 offset:32768
	ds_read_b128 v[192:195], v188 offset:33792
	ds_read_b128 v[196:199], v188 offset:34816
	ds_read_b128 v[200:203], v188 offset:35840
	ds_read_b128 v[204:207], v188 offset:36864
	ds_read_b128 v[208:211], v188 offset:37888
	ds_read_b128 v[212:215], v188 offset:38912
	ds_read_b128 v[216:219], v188 offset:39936
	global_load_lds_dwordx4 v[226:227], off
	v_lshl_add_u64 v[226:227], s[42:43], 0, v[142:143]
	s_mov_b32 m0, s69
	s_nop 0
	global_load_lds_dwordx4 v[226:227], off
	s_waitcnt vmcnt(8)
	s_waitcnt lgkmcnt(0)
	s_barrier
	s_waitcnt lgkmcnt(0)
	v_mfma_f32_16x16x32_bf16 v[124:127], v[128:131], v[176:179], v[124:127]
	v_mfma_f32_16x16x32_bf16 v[120:123], v[136:139], v[176:179], v[120:123]
	v_mfma_f32_16x16x32_bf16 v[108:111], v[128:131], v[196:199], v[108:111]
	v_mfma_f32_16x16x32_bf16 v[104:107], v[136:139], v[196:199], v[104:107]
	v_mfma_f32_16x16x32_bf16 v[92:95], v[128:131], v[204:207], v[92:95]
	v_mfma_f32_16x16x32_bf16 v[88:91], v[136:139], v[204:207], v[88:91]
	v_mfma_f32_16x16x32_bf16 v[76:79], v[128:131], v[212:215], v[76:79]
	v_mfma_f32_16x16x32_bf16 v[72:75], v[136:139], v[212:215], v[72:75]
	v_mfma_f32_16x16x32_bf16 v[124:127], v[132:135], v[192:195], v[124:127]
	v_mfma_f32_16x16x32_bf16 v[120:123], v[156:159], v[192:195], v[120:123]
	v_mfma_f32_16x16x32_bf16 v[108:111], v[132:135], v[200:203], v[108:111]
	v_mfma_f32_16x16x32_bf16 v[104:107], v[156:159], v[200:203], v[104:107]
	v_mfma_f32_16x16x32_bf16 v[92:95], v[132:135], v[208:211], v[92:95]
	v_mfma_f32_16x16x32_bf16 v[88:91], v[156:159], v[208:211], v[88:91]
	v_mfma_f32_16x16x32_bf16 v[76:79], v[132:135], v[216:219], v[76:79]
	v_mfma_f32_16x16x32_bf16 v[72:75], v[156:159], v[216:219], v[72:75]
	v_mfma_f32_16x16x32_bf16 v[116:119], v[160:163], v[176:179], v[116:119]
	v_mfma_f32_16x16x32_bf16 v[112:115], v[168:171], v[176:179], v[112:115]
	v_mfma_f32_16x16x32_bf16 v[100:103], v[160:163], v[196:199], v[100:103]
	v_mfma_f32_16x16x32_bf16 v[96:99], v[168:171], v[196:199], v[96:99]
	v_mfma_f32_16x16x32_bf16 v[84:87], v[160:163], v[204:207], v[84:87]
	v_mfma_f32_16x16x32_bf16 v[80:83], v[168:171], v[204:207], v[80:83]
	v_mfma_f32_16x16x32_bf16 v[68:71], v[160:163], v[212:215], v[68:71]
	v_mfma_f32_16x16x32_bf16 v[64:67], v[168:171], v[212:215], v[64:67]
	v_mfma_f32_16x16x32_bf16 v[116:119], v[164:167], v[192:195], v[116:119]
	v_mfma_f32_16x16x32_bf16 v[112:115], v[172:175], v[192:195], v[112:115]
	v_mfma_f32_16x16x32_bf16 v[100:103], v[164:167], v[200:203], v[100:103]
	v_mfma_f32_16x16x32_bf16 v[96:99], v[172:175], v[200:203], v[96:99]
	v_mfma_f32_16x16x32_bf16 v[84:87], v[164:167], v[208:211], v[84:87]
	v_mfma_f32_16x16x32_bf16 v[80:83], v[172:175], v[208:211], v[80:83]
	v_mfma_f32_16x16x32_bf16 v[68:71], v[164:167], v[216:219], v[68:71]
	v_mfma_f32_16x16x32_bf16 v[64:67], v[172:175], v[216:219], v[64:67]
	s_barrier
; #define PG8_STAGE(bufoff, gbase, voff) do { _Pragma("unroll") for (int _i = 0; _i < 2; ++_i) \
;         __builtin_amdgcn_global_load_lds((const unsigned*)((const char*)(gbase) + (voff)[_i]), (PG8_LAS unsigned*)(lds + (bufoff) + ldsw + _i * 8192), 16, 0, 0); } while (0)
; #define PG8_LDA(dst, b, h) do { _Pragma("unroll") for (int m = 0; m < 4; ++m) { if constexpr (FP8) dst##8[m] = PG8_LD32(lds + PG8_SA(b, h) + aoff + m * 2048); else { _Pragma("unroll") for (int k = 0; k < 2; ++k) dst[m][k] = *(const PG8_LAS bf16x8*)(lds + PG8_SA(b, h) + aoff + m * 2048 + k * 1024); } } } while (0)
; #define PG8_WAIT_V(n) asm volatile("s_waitcnt vmcnt(" #n ")" ::: "memory")
; #define PG8_WAIT_L(n) asm volatile("s_waitcnt lgkmcnt(" #n ")" ::: "memory")
; #define PG8_BAR __builtin_amdgcn_s_barrier()
; #define PG8_SCHED __builtin_amdgcn_sched_barrier(0)
; template <class Epi, class Sched, bool ALIGN_EPI = false, bool SP2 = false, bool FP8 = false>
; __device__ __forceinline__ void gemm_phase(PG8_LAS unsigned char* lds, const Gemm g, const Sched& S, const Epi& E, int wave_id) {
;     ...
;             PG8_LDA(At, 1, 1); PG8_STAGE(PG8_SB(1, 0), b3, voffB); PG8_STAGE(PG8_SB(1, 1), b3 + hstep, voffB); PG8_STAGE(PG8_SA(1, 0), a3, voffA);
;             PG8_WAIT_V(8); PG8_WAIT_L(0); PG8_BAR; PG8_MMA(1, 0, At, B0); PG8_MMA(1, 1, At, B1); PG8_BAR; PG8_SCHED;
;     ...
;         if constexpr (ALIGN_EPI) { if (wr == 0) PG8_BAR; }
	s_add_i32 s42, s78, s44
	v_lshl_add_u64 v[180:181], v[180:181], 0, s[14:15]
	s_mov_b32 m0, s42
	ds_read_b128 v[176:179], v188 offset:49152
	ds_read_b128 v[192:195], v188 offset:50176
	ds_read_b128 v[196:199], v188 offset:51200
	ds_read_b128 v[200:203], v188 offset:52224
	ds_read_b128 v[204:207], v188 offset:53248
	ds_read_b128 v[208:211], v188 offset:54272
	ds_read_b128 v[212:215], v188 offset:55296
	ds_read_b128 v[216:219], v188 offset:56320
	global_load_lds_dwordx4 v[180:181], off
	s_add_i32 m0, s42, 0x2000
	s_add_u32 s34, s34, 0x80080
	v_lshl_add_u64 v[180:181], v[220:221], 0, s[14:15]
	s_addc_u32 s35, s35, 0
	s_add_i32 s42, s79, s44
	global_load_lds_dwordx4 v[180:181], off
	v_lshl_add_u64 v[180:181], s[34:35], 0, v[144:145]
	s_mov_b32 m0, s42
	s_nop 0
	global_load_lds_dwordx4 v[180:181], off
	v_lshl_add_u64 v[180:181], s[34:35], 0, v[140:141]
	s_add_i32 m0, s42, 0x2000
	s_nop 0
	global_load_lds_dwordx4 v[180:181], off
	v_lshl_add_u64 v[180:181], v[222:223], 0, s[14:15]
	s_mov_b32 m0, s71
	s_nop 0
	global_load_lds_dwordx4 v[180:181], off
	v_lshl_add_u64 v[180:181], v[224:225], 0, s[14:15]
	s_mov_b32 m0, s74
	s_nop 0
	global_load_lds_dwordx4 v[180:181], off
	s_waitcnt vmcnt(8)
	s_waitcnt lgkmcnt(0)
	s_barrier
	s_waitcnt lgkmcnt(0)
	v_mfma_f32_16x16x32_bf16 v[60:63], v[128:131], v[176:179], v[60:63]
	v_mfma_f32_16x16x32_bf16 v[56:59], v[136:139], v[176:179], v[56:59]
	v_mfma_f32_16x16x32_bf16 v[44:47], v[128:131], v[196:199], v[44:47]
	v_mfma_f32_16x16x32_bf16 v[40:43], v[136:139], v[196:199], v[40:43]
	v_mfma_f32_16x16x32_bf16 v[28:31], v[128:131], v[204:207], v[28:31]
	v_mfma_f32_16x16x32_bf16 v[24:27], v[136:139], v[204:207], v[24:27]
	v_mfma_f32_16x16x32_bf16 v[12:15], v[128:131], v[212:215], v[12:15]
	v_mfma_f32_16x16x32_bf16 v[8:11], v[136:139], v[212:215], v[8:11]
	v_mfma_f32_16x16x32_bf16 v[60:63], v[132:135], v[192:195], v[60:63]
	v_mfma_f32_16x16x32_bf16 v[56:59], v[156:159], v[192:195], v[56:59]
	v_mfma_f32_16x16x32_bf16 v[44:47], v[132:135], v[200:203], v[44:47]
	v_mfma_f32_16x16x32_bf16 v[40:43], v[156:159], v[200:203], v[40:43]
	v_mfma_f32_16x16x32_bf16 v[28:31], v[132:135], v[208:211], v[28:31]
	v_mfma_f32_16x16x32_bf16 v[24:27], v[156:159], v[208:211], v[24:27]
	v_mfma_f32_16x16x32_bf16 v[12:15], v[132:135], v[216:219], v[12:15]
	v_mfma_f32_16x16x32_bf16 v[8:11], v[156:159], v[216:219], v[8:11]
	v_mfma_f32_16x16x32_bf16 v[52:55], v[160:163], v[176:179], v[52:55]
	v_mfma_f32_16x16x32_bf16 v[48:51], v[168:171], v[176:179], v[48:51]
	v_mfma_f32_16x16x32_bf16 v[36:39], v[160:163], v[196:199], v[36:39]
	v_mfma_f32_16x16x32_bf16 v[32:35], v[168:171], v[196:199], v[32:35]
	v_mfma_f32_16x16x32_bf16 v[20:23], v[160:163], v[204:207], v[20:23]
	v_mfma_f32_16x16x32_bf16 v[16:19], v[168:171], v[204:207], v[16:19]
	v_mfma_f32_16x16x32_bf16 v[4:7], v[160:163], v[212:215], v[4:7]
	v_mfma_f32_16x16x32_bf16 v[0:3], v[168:171], v[212:215], v[0:3]
	v_mfma_f32_16x16x32_bf16 v[52:55], v[164:167], v[192:195], v[52:55]
	v_mfma_f32_16x16x32_bf16 v[48:51], v[172:175], v[192:195], v[48:51]
	v_mfma_f32_16x16x32_bf16 v[36:39], v[164:167], v[200:203], v[36:39]
	v_mfma_f32_16x16x32_bf16 v[32:35], v[172:175], v[200:203], v[32:35]
	v_mfma_f32_16x16x32_bf16 v[20:23], v[164:167], v[208:211], v[20:23]
	v_mfma_f32_16x16x32_bf16 v[16:19], v[172:175], v[208:211], v[16:19]
	v_mfma_f32_16x16x32_bf16 v[4:7], v[164:167], v[216:219], v[4:7]
	v_mfma_f32_16x16x32_bf16 v[0:3], v[172:175], v[216:219], v[0:3]
	s_barrier
	s_add_i32 s95, s95, 2
	s_add_u32 s30, s30, 0x100
	s_addc_u32 s31, s31, 0
	s_add_u32 s93, s93, 0x100
	s_addc_u32 s94, s94, 0
	s_cmp_gt_u32 s95, 29
	s_cbranch_scc0 .LBB0_125
	s_and_b64 vcc, exec, s[16:17]
	s_cbranch_vccz .LBB0_128
	s_barrier

; #define PG8_STAGE(bufoff, gbase, voff) do { _Pragma("unroll") for (int _i = 0; _i < 2; ++_i) \
;         __builtin_amdgcn_global_load_lds((const unsigned*)((const char*)(gbase) + (voff)[_i]), (PG8_LAS unsigned*)(lds + (bufoff) + ldsw + _i * 8192), 16, 0, 0); } while (0)
; #define PG8_LDA(dst, b, h) do { _Pragma("unroll") for (int m = 0; m < 4; ++m) { if constexpr (FP8) dst##8[m] = PG8_LD32(lds + PG8_SA(b, h) + aoff + m * 2048); else { _Pragma("unroll") for (int k = 0; k < 2; ++k) dst[m][k] = *(const PG8_LAS bf16x8*)(lds + PG8_SA(b, h) + aoff + m * 2048 + k * 1024); } } } while (0)
; #define PG8_LDB(dst, b, h) do { _Pragma("unroll") for (int n = 0; n < 2; ++n) { if constexpr (FP8) dst##8[n] = PG8_LD32(lds + PG8_SB(b, h) + boff + n * 2048); else { _Pragma("unroll") for (int k = 0; k < 2; ++k) dst[n][k] = *(const PG8_LAS bf16x8*)(lds + PG8_SB(b, h) + boff + n * 2048 + k * 1024); } } } while (0)
; #define PG8_WAIT_V(n) asm volatile("s_waitcnt vmcnt(" #n ")" ::: "memory")
; #define PG8_WAIT_L(n) asm volatile("s_waitcnt lgkmcnt(" #n ")" ::: "memory")
; #define PG8_BAR __builtin_amdgcn_s_barrier()
; #define PG8_SCHED __builtin_amdgcn_sched_barrier(0)
; template <class Epi, class Sched, bool ALIGN_EPI = false, bool SP2 = false, bool FP8 = false>
; __device__ __forceinline__ void gemm_phase(PG8_LAS unsigned char* lds, const Gemm g, const Sched& S, const Epi& E, int wave_id) {
;     ...
;             PG8_LDB(B0, 0, 0); PG8_LDB(B1, 0, 1); PG8_SCHED; PG8_LDA(At, 0, 0); PG8_STAGE(PG8_SA(1, 1), a1 + hstep, voffA);
;             PG8_WAIT_V(8); PG8_WAIT_L(0); PG8_BAR; PG8_MMA(0, 0, At, B0); PG8_MMA(0, 1, At, B1); PG8_BAR; PG8_SCHED;
;             PG8_LDA(At, 0, 1); PG8_STAGE(PG8_SB(0, 0), b2, voffB); PG8_STAGE(PG8_SB(0, 1), b2 + hstep, voffB); PG8_STAGE(PG8_SA(0, 0), a2, voffA);
;             PG8_WAIT_V(8); PG8_WAIT_L(0); PG8_BAR; PG8_MMA(1, 0, At, B0); PG8_MMA(1, 1, At, B1); PG8_BAR; PG8_SCHED;
.LBB0_329:
	ds_read_b128 v[128:131], v209
	ds_read_b128 v[132:135], v209 offset:1024
	ds_read_b128 v[136:139], v209 offset:2048
	ds_read_b128 v[140:143], v209 offset:3072
	ds_read_b128 v[144:147], v210
	ds_read_b128 v[148:151], v210 offset:1024
	ds_read_b128 v[152:155], v210 offset:2048
	ds_read_b128 v[156:159], v210 offset:3072
	s_add_u32 s28, s26, 0xfff80080
	s_addc_u32 s29, s27, -1
	s_cmp_eq_u32 s64, 28
	s_cselect_b32 s31, s17, s29
	s_cselect_b32 s30, s23, s28
	s_cselect_b32 s29, s15, s63
	s_cselect_b32 s28, s61, s62
	v_lshl_add_u64 v[216:217], s[26:27], 0, v[184:185]
	s_add_i32 m0, s25, 0xc000
	ds_read_b128 v[160:163], v211
	ds_read_b128 v[164:167], v211 offset:1024
	ds_read_b128 v[168:171], v211 offset:2048
	ds_read_b128 v[172:175], v211 offset:3072
	ds_read_b128 v[192:195], v211 offset:4096
	ds_read_b128 v[196:199], v211 offset:5120
	ds_read_b128 v[200:203], v211 offset:6144
	ds_read_b128 v[212:215], v211 offset:7168
	global_load_lds_dwordx4 v[216:217], off
	v_lshl_add_u64 v[216:217], s[26:27], 0, v[186:187]
	s_add_i32 m0, s25, 0xe000
	s_nop 0
	global_load_lds_dwordx4 v[216:217], off
	s_waitcnt vmcnt(8)
	s_waitcnt lgkmcnt(0)
	s_barrier
	s_waitcnt lgkmcnt(0)
	v_mfma_f32_16x16x32_bf16 v[124:127], v[128:131], v[160:163], v[124:127]
	v_mfma_f32_16x16x32_bf16 v[120:123], v[136:139], v[160:163], v[120:123]
	v_mfma_f32_16x16x32_bf16 v[108:111], v[128:131], v[168:171], v[108:111]
	v_mfma_f32_16x16x32_bf16 v[104:107], v[136:139], v[168:171], v[104:107]
	v_mfma_f32_16x16x32_bf16 v[92:95], v[128:131], v[192:195], v[92:95]
	v_mfma_f32_16x16x32_bf16 v[88:91], v[136:139], v[192:195], v[88:91]
	v_mfma_f32_16x16x32_bf16 v[76:79], v[128:131], v[200:203], v[76:79]
	v_mfma_f32_16x16x32_bf16 v[72:75], v[136:139], v[200:203], v[72:75]
	v_mfma_f32_16x16x32_bf16 v[124:127], v[132:135], v[164:167], v[124:127]
	v_mfma_f32_16x16x32_bf16 v[120:123], v[140:143], v[164:167], v[120:123]
	v_mfma_f32_16x16x32_bf16 v[108:111], v[132:135], v[172:175], v[108:111]
	v_mfma_f32_16x16x32_bf16 v[104:107], v[140:143], v[172:175], v[104:107]
	v_mfma_f32_16x16x32_bf16 v[92:95], v[132:135], v[196:199], v[92:95]
	v_mfma_f32_16x16x32_bf16 v[88:91], v[140:143], v[196:199], v[88:91]
	v_mfma_f32_16x16x32_bf16 v[76:79], v[132:135], v[212:215], v[76:79]
	v_mfma_f32_16x16x32_bf16 v[72:75], v[140:143], v[212:215], v[72:75]
	v_mfma_f32_16x16x32_bf16 v[116:119], v[144:147], v[160:163], v[116:119]
	v_mfma_f32_16x16x32_bf16 v[112:115], v[152:155], v[160:163], v[112:115]
	v_mfma_f32_16x16x32_bf16 v[100:103], v[144:147], v[168:171], v[100:103]
	v_mfma_f32_16x16x32_bf16 v[96:99], v[152:155], v[168:171], v[96:99]
	v_mfma_f32_16x16x32_bf16 v[84:87], v[144:147], v[192:195], v[84:87]
	v_mfma_f32_16x16x32_bf16 v[80:83], v[152:155], v[192:195], v[80:83]
	v_mfma_f32_16x16x32_bf16 v[68:71], v[144:147], v[200:203], v[68:71]
	v_mfma_f32_16x16x32_bf16 v[64:67], v[152:155], v[200:203], v[64:67]
	v_mfma_f32_16x16x32_bf16 v[116:119], v[148:151], v[164:167], v[116:119]
	v_mfma_f32_16x16x32_bf16 v[112:115], v[156:159], v[164:167], v[112:115]
	v_mfma_f32_16x16x32_bf16 v[100:103], v[148:151], v[172:175], v[100:103]
	v_mfma_f32_16x16x32_bf16 v[96:99], v[156:159], v[172:175], v[96:99]
	v_mfma_f32_16x16x32_bf16 v[84:87], v[148:151], v[196:199], v[84:87]
	v_mfma_f32_16x16x32_bf16 v[80:83], v[156:159], v[196:199], v[80:83]
	v_mfma_f32_16x16x32_bf16 v[68:71], v[148:151], v[212:215], v[68:71]
	v_mfma_f32_16x16x32_bf16 v[64:67], v[156:159], v[212:215], v[64:67]
	s_barrier
	s_add_i32 s65, s59, s35
	v_lshl_add_u64 v[216:217], s[28:29], 0, v[178:179]
	s_mov_b32 m0, s65
	ds_read_b128 v[160:163], v211 offset:16384
	ds_read_b128 v[164:167], v211 offset:17408
	ds_read_b128 v[168:171], v211 offset:18432
	ds_read_b128 v[172:175], v211 offset:19456
	ds_read_b128 v[192:195], v211 offset:20480
	ds_read_b128 v[196:199], v211 offset:21504
	ds_read_b128 v[200:203], v211 offset:22528
	ds_read_b128 v[212:215], v211 offset:23552
	global_load_lds_dwordx4 v[216:217], off
	s_add_i32 m0, s65, 0x2000
	s_add_u32 s66, s28, 0x80000
	v_lshl_add_u64 v[218:219], s[28:29], 0, v[182:183]
	s_addc_u32 s67, s29, 0
	s_add_i32 s65, s60, s35
	global_load_lds_dwordx4 v[218:219], off
	v_lshl_add_u64 v[220:221], s[66:67], 0, v[178:179]
	s_mov_b32 m0, s65
	v_lshl_add_u64 v[222:223], s[30:31], 0, v[180:181]
	global_load_lds_dwordx4 v[220:221], off
	v_lshl_add_u64 v[220:221], s[66:67], 0, v[182:183]
	s_add_i32 m0, s65, 0x2000
	s_nop 0
	global_load_lds_dwordx4 v[220:221], off
	v_lshl_add_u64 v[220:221], s[30:31], 0, v[176:177]
	s_mov_b32 m0, s25
	s_nop 0
	global_load_lds_dwordx4 v[220:221], off
	s_mov_b32 m0, s36
	s_nop 0
	global_load_lds_dwordx4 v[222:223], off
	s_waitcnt vmcnt(8)
	s_waitcnt lgkmcnt(0)
	s_barrier
; #define PG8_STAGE(bufoff, gbase, voff) do { _Pragma("unroll") for (int _i = 0; _i < 2; ++_i) \
;         __builtin_amdgcn_global_load_lds((const unsigned*)((const char*)(gbase) + (voff)[_i]), (PG8_LAS unsigned*)(lds + (bufoff) + ldsw + _i * 8192), 16, 0, 0); } while (0)
; #define PG8_LDA(dst, b, h) do { _Pragma("unroll") for (int m = 0; m < 4; ++m) { if constexpr (FP8) dst##8[m] = PG8_LD32(lds + PG8_SA(b, h) + aoff + m * 2048); else { _Pragma("unroll") for (int k = 0; k < 2; ++k) dst[m][k] = *(const PG8_LAS bf16x8*)(lds + PG8_SA(b, h) + aoff + m * 2048 + k * 1024); } } } while (0)
; #define PG8_LDB(dst, b, h) do { _Pragma("unroll") for (int n = 0; n < 2; ++n) { if constexpr (FP8) dst##8[n] = PG8_LD32(lds + PG8_SB(b, h) + boff + n * 2048); else { _Pragma("unroll") for (int k = 0; k < 2; ++k) dst[n][k] = *(const PG8_LAS bf16x8*)(lds + PG8_SB(b, h) + boff + n * 2048 + k * 1024); } } } while (0)
; #define PG8_WAIT_V(n) asm volatile("s_waitcnt vmcnt(" #n ")" ::: "memory")
; #define PG8_WAIT_L(n) asm volatile("s_waitcnt lgkmcnt(" #n ")" ::: "memory")
; #define PG8_BAR __builtin_amdgcn_s_barrier()
; #define PG8_SCHED __builtin_amdgcn_sched_barrier(0)
; template <class Epi, class Sched, bool ALIGN_EPI = false, bool SP2 = false, bool FP8 = false>
; __device__ __forceinline__ void gemm_phase(PG8_LAS unsigned char* lds, const Gemm g, const Sched& S, const Epi& E, int wave_id) {
;     ...
;             PG8_WAIT_V(8); PG8_WAIT_L(0); PG8_BAR; PG8_MMA(1, 0, At, B0); PG8_MMA(1, 1, At, B1); PG8_BAR; PG8_SCHED;
;             PG8_LDB(B0, 1, 0); PG8_LDB(B1, 1, 1); PG8_SCHED; PG8_LDA(At, 1, 0); PG8_STAGE(PG8_SA(0, 1), a2 + hstep, voffA);
;             PG8_WAIT_V(8); PG8_WAIT_L(0); PG8_BAR; PG8_MMA(0, 0, At, B0); PG8_MMA(0, 1, At, B1); PG8_BAR; PG8_SCHED;
	s_waitcnt lgkmcnt(0)
	v_mfma_f32_16x16x32_bf16 v[60:63], v[128:131], v[160:163], v[60:63]
	v_mfma_f32_16x16x32_bf16 v[56:59], v[136:139], v[160:163], v[56:59]
	v_mfma_f32_16x16x32_bf16 v[44:47], v[128:131], v[168:171], v[44:47]
	v_mfma_f32_16x16x32_bf16 v[40:43], v[136:139], v[168:171], v[40:43]
	v_mfma_f32_16x16x32_bf16 v[28:31], v[128:131], v[192:195], v[28:31]
	v_mfma_f32_16x16x32_bf16 v[24:27], v[136:139], v[192:195], v[24:27]
	v_mfma_f32_16x16x32_bf16 v[12:15], v[128:131], v[200:203], v[12:15]
	v_mfma_f32_16x16x32_bf16 v[8:11], v[136:139], v[200:203], v[8:11]
	v_mfma_f32_16x16x32_bf16 v[60:63], v[132:135], v[164:167], v[60:63]
	v_mfma_f32_16x16x32_bf16 v[56:59], v[140:143], v[164:167], v[56:59]
	v_mfma_f32_16x16x32_bf16 v[44:47], v[132:135], v[172:175], v[44:47]
	v_mfma_f32_16x16x32_bf16 v[40:43], v[140:143], v[172:175], v[40:43]
	v_mfma_f32_16x16x32_bf16 v[28:31], v[132:135], v[196:199], v[28:31]
	v_mfma_f32_16x16x32_bf16 v[24:27], v[140:143], v[196:199], v[24:27]
	v_mfma_f32_16x16x32_bf16 v[12:15], v[132:135], v[212:215], v[12:15]
	v_mfma_f32_16x16x32_bf16 v[8:11], v[140:143], v[212:215], v[8:11]
	v_mfma_f32_16x16x32_bf16 v[52:55], v[144:147], v[160:163], v[52:55]
	v_mfma_f32_16x16x32_bf16 v[48:51], v[152:155], v[160:163], v[48:51]
	v_mfma_f32_16x16x32_bf16 v[36:39], v[144:147], v[168:171], v[36:39]
	v_mfma_f32_16x16x32_bf16 v[32:35], v[152:155], v[168:171], v[32:35]
	v_mfma_f32_16x16x32_bf16 v[20:23], v[144:147], v[192:195], v[20:23]
	v_mfma_f32_16x16x32_bf16 v[16:19], v[152:155], v[192:195], v[16:19]
	v_mfma_f32_16x16x32_bf16 v[4:7], v[144:147], v[200:203], v[4:7]
	v_mfma_f32_16x16x32_bf16 v[0:3], v[152:155], v[200:203], v[0:3]
	v_mfma_f32_16x16x32_bf16 v[52:55], v[148:151], v[164:167], v[52:55]
	v_mfma_f32_16x16x32_bf16 v[48:51], v[156:159], v[164:167], v[48:51]
	v_mfma_f32_16x16x32_bf16 v[36:39], v[148:151], v[172:175], v[36:39]
	v_mfma_f32_16x16x32_bf16 v[32:35], v[156:159], v[172:175], v[32:35]
	v_mfma_f32_16x16x32_bf16 v[20:23], v[148:151], v[196:199], v[20:23]
	v_mfma_f32_16x16x32_bf16 v[16:19], v[156:159], v[196:199], v[16:19]
	v_mfma_f32_16x16x32_bf16 v[4:7], v[148:151], v[212:215], v[4:7]
	v_mfma_f32_16x16x32_bf16 v[0:3], v[156:159], v[212:215], v[0:3]
	s_barrier
	s_add_i32 s65, 0, 0x18000
	s_add_i32 s66, 0, 0x1c000
	v_add_u32_e32 v140, s65, v205
	v_add_u32_e32 v156, s66, v205
	ds_read_b128 v[128:131], v140
	ds_read_b128 v[132:135], v140 offset:1024
	ds_read_b128 v[136:139], v140 offset:2048
	ds_read_b128 v[140:143], v140 offset:3072
	ds_read_b128 v[144:147], v156
	ds_read_b128 v[148:151], v156 offset:1024
	ds_read_b128 v[152:155], v156 offset:2048
	ds_read_b128 v[156:159], v156 offset:3072
	s_add_u32 s30, s30, 0x80000
	s_addc_u32 s31, s31, 0
	s_mov_b32 m0, s37
	v_lshl_add_u64 v[224:225], s[30:31], 0, v[176:177]
	ds_read_b128 v[160:163], v211 offset:32768
	ds_read_b128 v[164:167], v211 offset:33792
	ds_read_b128 v[168:171], v211 offset:34816
	ds_read_b128 v[172:175], v211 offset:35840
	ds_read_b128 v[192:195], v211 offset:36864
	ds_read_b128 v[196:199], v211 offset:37888
	ds_read_b128 v[200:203], v211 offset:38912
	ds_read_b128 v[212:215], v211 offset:39936
	global_load_lds_dwordx4 v[224:225], off
	v_lshl_add_u64 v[224:225], s[30:31], 0, v[180:181]
	s_mov_b32 m0, s44
	s_nop 0
	global_load_lds_dwordx4 v[224:225], off
	s_waitcnt vmcnt(8)
	s_waitcnt lgkmcnt(0)
	s_barrier
	s_waitcnt lgkmcnt(0)
	v_mfma_f32_16x16x32_bf16 v[124:127], v[128:131], v[160:163], v[124:127]
	v_mfma_f32_16x16x32_bf16 v[120:123], v[136:139], v[160:163], v[120:123]
	v_mfma_f32_16x16x32_bf16 v[108:111], v[128:131], v[168:171], v[108:111]
	v_mfma_f32_16x16x32_bf16 v[104:107], v[136:139], v[168:171], v[104:107]
	v_mfma_f32_16x16x32_bf16 v[92:95], v[128:131], v[192:195], v[92:95]
	v_mfma_f32_16x16x32_bf16 v[88:91], v[136:139], v[192:195], v[88:91]
	v_mfma_f32_16x16x32_bf16 v[76:79], v[128:131], v[200:203], v[76:79]
	v_mfma_f32_16x16x32_bf16 v[72:75], v[136:139], v[200:203], v[72:75]
	v_mfma_f32_16x16x32_bf16 v[124:127], v[132:135], v[164:167], v[124:127]
	v_mfma_f32_16x16x32_bf16 v[120:123], v[140:143], v[164:167], v[120:123]
	v_mfma_f32_16x16x32_bf16 v[108:111], v[132:135], v[172:175], v[108:111]
	v_mfma_f32_16x16x32_bf16 v[104:107], v[140:143], v[172:175], v[104:107]
	v_mfma_f32_16x16x32_bf16 v[92:95], v[132:135], v[196:199], v[92:95]
	v_mfma_f32_16x16x32_bf16 v[88:91], v[140:143], v[196:199], v[88:91]
	v_mfma_f32_16x16x32_bf16 v[76:79], v[132:135], v[212:215], v[76:79]
	v_mfma_f32_16x16x32_bf16 v[72:75], v[140:143], v[212:215], v[72:75]
	v_mfma_f32_16x16x32_bf16 v[116:119], v[144:147], v[160:163], v[116:119]
	v_mfma_f32_16x16x32_bf16 v[112:115], v[152:155], v[160:163], v[112:115]
	v_mfma_f32_16x16x32_bf16 v[100:103], v[144:147], v[168:171], v[100:103]
	v_mfma_f32_16x16x32_bf16 v[96:99], v[152:155], v[168:171], v[96:99]
	v_mfma_f32_16x16x32_bf16 v[84:87], v[144:147], v[192:195], v[84:87]
	v_mfma_f32_16x16x32_bf16 v[80:83], v[152:155], v[192:195], v[80:83]
	v_mfma_f32_16x16x32_bf16 v[68:71], v[144:147], v[200:203], v[68:71]
	v_mfma_f32_16x16x32_bf16 v[64:67], v[152:155], v[200:203], v[64:67]
	v_mfma_f32_16x16x32_bf16 v[116:119], v[148:151], v[164:167], v[116:119]
	v_mfma_f32_16x16x32_bf16 v[112:115], v[156:159], v[164:167], v[112:115]
	v_mfma_f32_16x16x32_bf16 v[100:103], v[148:151], v[172:175], v[100:103]
	v_mfma_f32_16x16x32_bf16 v[96:99], v[156:159], v[172:175], v[96:99]
	v_mfma_f32_16x16x32_bf16 v[84:87], v[148:151], v[196:199], v[84:87]
	v_mfma_f32_16x16x32_bf16 v[80:83], v[156:159], v[196:199], v[80:83]
	v_mfma_f32_16x16x32_bf16 v[68:71], v[148:151], v[212:215], v[68:71]
	v_mfma_f32_16x16x32_bf16 v[64:67], v[156:159], v[212:215], v[64:67]
	s_barrier
; #define PG8_STAGE(bufoff, gbase, voff) do { _Pragma("unroll") for (int _i = 0; _i < 2; ++_i) \
;         __builtin_amdgcn_global_load_lds((const unsigned*)((const char*)(gbase) + (voff)[_i]), (PG8_LAS unsigned*)(lds + (bufoff) + ldsw + _i * 8192), 16, 0, 0); } while (0)
; #define PG8_LDA(dst, b, h) do { _Pragma("unroll") for (int m = 0; m < 4; ++m) { if constexpr (FP8) dst##8[m] = PG8_LD32(lds + PG8_SA(b, h) + aoff + m * 2048); else { _Pragma("unroll") for (int k = 0; k < 2; ++k) dst[m][k] = *(const PG8_LAS bf16x8*)(lds + PG8_SA(b, h) + aoff + m * 2048 + k * 1024); } } } while (0)
; #define PG8_WAIT_V(n) asm volatile("s_waitcnt vmcnt(" #n ")" ::: "memory")
; #define PG8_WAIT_L(n) asm volatile("s_waitcnt lgkmcnt(" #n ")" ::: "memory")
; #define PG8_BAR __builtin_amdgcn_s_barrier()
; #define PG8_SCHED __builtin_amdgcn_sched_barrier(0)
; template <class Epi, class Sched, bool ALIGN_EPI = false, bool SP2 = false, bool FP8 = false>
; __device__ __forceinline__ void gemm_phase(PG8_LAS unsigned char* lds, const Gemm g, const Sched& S, const Epi& E, int wave_id) {
;     ...
;             PG8_LDA(At, 1, 1); PG8_STAGE(PG8_SB(1, 0), b3, voffB); PG8_STAGE(PG8_SB(1, 1), b3 + hstep, voffB); PG8_STAGE(PG8_SA(1, 0), a3, voffA);
;             PG8_WAIT_V(8); PG8_WAIT_L(0); PG8_BAR; PG8_MMA(1, 0, At, B0); PG8_MMA(1, 1, At, B1); PG8_BAR; PG8_SCHED;
	s_add_i32 s30, s65, s35
	v_lshl_add_u64 v[216:217], v[216:217], 0, s[12:13]
	s_mov_b32 m0, s30
	ds_read_b128 v[160:163], v211 offset:49152
	ds_read_b128 v[164:167], v211 offset:50176
	ds_read_b128 v[168:171], v211 offset:51200
	ds_read_b128 v[172:175], v211 offset:52224
	ds_read_b128 v[192:195], v211 offset:53248
	ds_read_b128 v[196:199], v211 offset:54272
	ds_read_b128 v[200:203], v211 offset:55296
	ds_read_b128 v[212:215], v211 offset:56320
	global_load_lds_dwordx4 v[216:217], off
	s_add_i32 m0, s30, 0x2000
	s_add_u32 s28, s28, 0x80080
	v_lshl_add_u64 v[216:217], v[218:219], 0, s[12:13]
	s_addc_u32 s29, s29, 0
	s_add_i32 s30, s66, s35
	global_load_lds_dwordx4 v[216:217], off
	v_lshl_add_u64 v[216:217], s[28:29], 0, v[178:179]
	s_mov_b32 m0, s30
	s_nop 0
	global_load_lds_dwordx4 v[216:217], off
	v_lshl_add_u64 v[216:217], s[28:29], 0, v[182:183]
	s_add_i32 m0, s30, 0x2000
	s_nop 0
	global_load_lds_dwordx4 v[216:217], off
	v_lshl_add_u64 v[216:217], v[220:221], 0, s[12:13]
	s_mov_b32 m0, s54
	s_nop 0
	global_load_lds_dwordx4 v[216:217], off
	v_lshl_add_u64 v[216:217], v[222:223], 0, s[12:13]
	s_mov_b32 m0, s55
	s_nop 0
	global_load_lds_dwordx4 v[216:217], off
	s_waitcnt vmcnt(8)
	s_waitcnt lgkmcnt(0)
	s_barrier
	s_waitcnt lgkmcnt(0)
	v_mfma_f32_16x16x32_bf16 v[60:63], v[128:131], v[160:163], v[60:63]
	v_mfma_f32_16x16x32_bf16 v[56:59], v[136:139], v[160:163], v[56:59]
	v_mfma_f32_16x16x32_bf16 v[44:47], v[128:131], v[168:171], v[44:47]
	v_mfma_f32_16x16x32_bf16 v[40:43], v[136:139], v[168:171], v[40:43]
	v_mfma_f32_16x16x32_bf16 v[28:31], v[128:131], v[192:195], v[28:31]
	v_mfma_f32_16x16x32_bf16 v[24:27], v[136:139], v[192:195], v[24:27]
	v_mfma_f32_16x16x32_bf16 v[12:15], v[128:131], v[200:203], v[12:15]
	v_mfma_f32_16x16x32_bf16 v[8:11], v[136:139], v[200:203], v[8:11]
	v_mfma_f32_16x16x32_bf16 v[60:63], v[132:135], v[164:167], v[60:63]
	v_mfma_f32_16x16x32_bf16 v[56:59], v[140:143], v[164:167], v[56:59]
	v_mfma_f32_16x16x32_bf16 v[44:47], v[132:135], v[172:175], v[44:47]
	v_mfma_f32_16x16x32_bf16 v[40:43], v[140:143], v[172:175], v[40:43]
	v_mfma_f32_16x16x32_bf16 v[28:31], v[132:135], v[196:199], v[28:31]
	v_mfma_f32_16x16x32_bf16 v[24:27], v[140:143], v[196:199], v[24:27]
	v_mfma_f32_16x16x32_bf16 v[12:15], v[132:135], v[212:215], v[12:15]
	v_mfma_f32_16x16x32_bf16 v[8:11], v[140:143], v[212:215], v[8:11]
	v_mfma_f32_16x16x32_bf16 v[52:55], v[144:147], v[160:163], v[52:55]
	v_mfma_f32_16x16x32_bf16 v[48:51], v[152:155], v[160:163], v[48:51]
	v_mfma_f32_16x16x32_bf16 v[36:39], v[144:147], v[168:171], v[36:39]
	v_mfma_f32_16x16x32_bf16 v[32:35], v[152:155], v[168:171], v[32:35]
	v_mfma_f32_16x16x32_bf16 v[20:23], v[144:147], v[192:195], v[20:23]
	v_mfma_f32_16x16x32_bf16 v[16:19], v[152:155], v[192:195], v[16:19]
	v_mfma_f32_16x16x32_bf16 v[4:7], v[144:147], v[200:203], v[4:7]
	v_mfma_f32_16x16x32_bf16 v[0:3], v[152:155], v[200:203], v[0:3]
	v_mfma_f32_16x16x32_bf16 v[52:55], v[148:151], v[164:167], v[52:55]
	v_mfma_f32_16x16x32_bf16 v[48:51], v[156:159], v[164:167], v[48:51]
	v_mfma_f32_16x16x32_bf16 v[36:39], v[148:151], v[172:175], v[36:39]
	v_mfma_f32_16x16x32_bf16 v[32:35], v[156:159], v[172:175], v[32:35]
	v_mfma_f32_16x16x32_bf16 v[20:23], v[148:151], v[196:199], v[20:23]
	v_mfma_f32_16x16x32_bf16 v[16:19], v[156:159], v[196:199], v[16:19]
	v_mfma_f32_16x16x32_bf16 v[4:7], v[148:151], v[212:215], v[4:7]
	v_mfma_f32_16x16x32_bf16 v[0:3], v[156:159], v[212:215], v[0:3]
	s_barrier
	s_add_i32 s64, s64, 2
	s_add_u32 s26, s26, 0x100
	s_addc_u32 s27, s27, 0
	s_add_u32 s62, s62, 0x100
	s_addc_u32 s63, s63, 0
	s_cmp_gt_u32 s64, 29
	s_cbranch_scc0 .LBB0_329
;     __device__ __forceinline__ void operator()(const f32x4 (&acc)[2][2][4][2], const Unit& u, int wr, int wc, int fr, int fq) const {
;         const int row0 = u.pm * BM + wr * 64 + fr, col0 = u.pn * BM + wc * 32 + 8 * fq;
; #pragma unroll
;         for (int ai = 0; ai < 2; ++ai) {
;             f32x4 rv[4][2][2];
; #pragma unroll
;             for (int m = 0; m < 4; ++m)
; #pragma unroll
;                 for (int bj = 0; bj < 2; ++bj) {
;                     const size_t off = (size_t)(row0 + ai * HALF + m * 16) * DM + col0 + bj * HALF;
;                     if (RES_BF16) {
;                         const v4u t = *(const v4u*)(Yb + off);
;                         rv[m][bj][0] = (f32x4){__builtin_bit_cast(float, t.x << 16), __builtin_bit_cast(float, t.x & 0xffff0000u), __builtin_bit_cast(float, t.y << 16), __builtin_bit_cast(float, t.y & 0xffff0000u)};
;                         rv[m][bj][1] = (f32x4){__builtin_bit_cast(float, t.z << 16), __builtin_bit_cast(float, t.z & 0xffff0000u), __builtin_bit_cast(float, t.w << 16), __builtin_bit_cast(float, t.w & 0xffff0000u)};
;                     } else { rv[m][bj][0] = *(const f32x4*)(R + off); rv[m][bj][1] = *(const f32x4*)(R + off + 4); }
;                 }
;             asm volatile("" ::: "memory");
; #pragma unroll
;             for (int m = 0; m < 4; ++m) {
;                 const int row = row0 + ai * HALF + m * 16; float s = 0.f;
; #pragma unroll
;                 for (int bj = 0; bj < 2; ++bj) {
;                     const size_t off = (size_t)row * DM + col0 + bj * HALF;
;                     const f32x4 v0 = acc[ai][bj][m][0] * ascale + rv[m][bj][0], v1 = acc[ai][bj][m][1] * ascale + rv[m][bj][1];
;                     { v4u w; w.x = cvt_pk_bf16(v0[0], v0[1]); w.y = cvt_pk_bf16(v0[2], v0[3]); w.z = cvt_pk_bf16(v1[0], v1[1]); w.w = cvt_pk_bf16(v1[2], v1[3]); *(v4u*)(Yb + off) = w; }
;                     if (!RES_BF16) { int w0 = __builtin_amdgcn_cvt_pk_fp8_f32(v0[0], v0[1], 0, false); w0 = __builtin_amdgcn_cvt_pk_fp8_f32(v0[2], v0[3], w0, true);
;                         int w1 = __builtin_amdgcn_cvt_pk_fp8_f32(v1[0], v1[1], 0, false); w1 = __builtin_amdgcn_cvt_pk_fp8_f32(v1[2], v1[3], w1, true);
;                         *(v2u*)(Y8 + off) = (v2u){(unsigned)w0, (unsigned)w1}; }
	v_lshl_add_u32 v196, s22, 8, v204
	v_lshl_or_b32 v192, s24, 8, v208
	v_ashrrev_i32_e32 v193, 31, v192
	v_ashrrev_i32_e32 v197, 31, v196
	v_lshl_add_u64 v[194:195], v[192:193], 2, s[52:53]
	v_lshlrev_b64 v[128:129], 13, v[196:197]
	v_lshl_add_u64 v[128:129], v[194:195], 0, v[128:129]
	global_load_dwordx4 v[212:215], v[128:129], off
	global_load_dwordx4 v[216:219], v[128:129], off offset:16
	global_load_dwordx4 v[220:223], v[128:129], off offset:512
	global_load_dwordx4 v[224:227], v[128:129], off offset:528
	v_or_b32_e32 v202, 16, v196
	v_or_b32_e32 v200, 32, v196
	v_or_b32_e32 v198, 48, v196
	v_ashrrev_i32_e32 v203, 31, v202
	v_ashrrev_i32_e32 v201, 31, v200
	v_ashrrev_i32_e32 v199, 31, v198
	v_lshlrev_b64 v[128:129], 13, v[202:203]
	v_lshlrev_b64 v[130:131], 13, v[200:201]
	v_lshlrev_b64 v[132:133], 13, v[198:199]
	v_lshl_add_u64 v[128:129], v[194:195], 0, v[128:129]
	v_lshl_add_u64 v[130:131], v[194:195], 0, v[130:131]
	v_lshl_add_u64 v[132:133], v[194:195], 0, v[132:133]
	global_load_dwordx4 v[168:171], v[128:129], off offset:16
	global_load_dwordx4 v[172:175], v[128:129], off
	global_load_dwordx4 v[160:163], v[128:129], off offset:528
	global_load_dwordx4 v[164:167], v[128:129], off offset:512
	global_load_dwordx4 v[152:155], v[130:131], off offset:16
	global_load_dwordx4 v[156:159], v[130:131], off
	global_load_dwordx4 v[144:147], v[130:131], off offset:528
	global_load_dwordx4 v[148:151], v[130:131], off offset:512
	global_load_dwordx4 v[136:139], v[132:133], off offset:16
	global_load_dwordx4 v[140:143], v[132:133], off
	s_nop 0
	global_load_dwordx4 v[128:131], v[132:133], off offset:528
	s_nop 0
	global_load_dwordx4 v[132:135], v[132:133], off offset:512
	v_mov_b32_e32 v228, 0
	v_lshlrev_b64 v[232:233], 11, v[196:197]
	v_mov_b32_e32 v229, 0
	v_lshl_add_u64 v[232:233], v[232:233], 0, v[192:193]
	v_lshl_add_u64 v[234:235], v[232:233], 1, s[38:39]
	v_mov_b32_e32 v230, 0
	v_mov_b32_e32 v231, 0
	v_lshl_add_u64 v[236:237], s[6:7], 0, v[232:233]
	v_or_b32_e32 v232, 0x80, v232
	s_waitcnt vmcnt(0)
	v_pk_add_f32 v[126:127], v[126:127], v[214:215]
	v_pk_add_f32 v[124:125], v[124:125], v[212:213]
	v_pk_add_f32 v[118:119], v[118:119], v[222:223]
	v_pk_add_f32 v[116:117], v[116:117], v[220:221]
	v_pk_add_f32 v[122:123], v[122:123], v[218:219]
	v_pk_add_f32 v[120:121], v[120:121], v[216:217]
	v_pk_add_f32 v[214:215], v[112:113], v[224:225]
	v_cvt_pk_bf16_f32 v112, v124, v125
	v_cvt_pk_fp8_f32 v228, v124, v125
	v_mul_f32_e32 v125, v125, v125
	v_mul_f32_e32 v216, v127, v127
	v_mul_f32_e32 v218, v117, v117
	v_mul_f32_e32 v219, v119, v119
	v_pk_add_f32 v[212:213], v[114:115], v[226:227]
	v_cvt_pk_bf16_f32 v113, v126, v127
	v_cvt_pk_bf16_f32 v114, v120, v121
	v_cvt_pk_fp8_f32 v229, v120, v121
	v_mul_f32_e32 v121, v121, v121
	v_mul_f32_e32 v220, v215, v215
	v_fmac_f32_e32 v125, v124, v124
	v_fmac_f32_e32 v216, v126, v126
	v_fmac_f32_e32 v218, v116, v116
	v_fmac_f32_e32 v219, v118, v118
	v_cvt_pk_bf16_f32 v115, v122, v123
	v_mul_f32_e32 v217, v123, v123
	v_mul_f32_e32 v221, v213, v213
	global_store_dwordx4 v[234:235], v[112:115], off
	v_fmac_f32_e32 v121, v120, v120
	v_fmac_f32_e32 v220, v214, v214
	v_add_f32_e32 v112, v125, v216
	v_add_f32_e32 v113, v218, v219
	v_fmac_f32_e32 v217, v122, v122
	v_fmac_f32_e32 v221, v212, v212
	v_add_f32_e32 v112, v121, v112
	v_add_f32_e32 v113, v220, v113
	v_add_f32_e32 v112, v217, v112
	v_add_f32_e32 v113, v221, v113
	v_add_f32_e32 v112, v112, v113
	ds_bpermute_b32 v113, v206, v112
	v_cvt_pk_fp8_f32 v230, v116, v117
	v_cvt_pk_fp8_f32 v231, v214, v215
	v_cvt_pk_fp8_f32 v228, v126, v127 op_sel:[0,0,1]
	v_cvt_pk_fp8_f32 v229, v122, v123 op_sel:[0,0,1]
	s_waitcnt lgkmcnt(0)
	v_add_f32_e32 v112, v112, v113
	ds_bpermute_b32 v113, v207, v112
	v_cvt_pk_fp8_f32 v230, v118, v119 op_sel:[0,0,1]
	v_cvt_pk_fp8_f32 v231, v212, v213 op_sel:[0,0,1]
	global_store_dwordx2 v[236:237], v[228:229], off
	v_cvt_pk_bf16_f32 v114, v116, v117
	v_cvt_pk_bf16_f32 v115, v118, v119
	v_lshl_add_u64 v[118:119], v[232:233], 1, s[38:39]
	v_cvt_pk_bf16_f32 v116, v214, v215
	v_cvt_pk_bf16_f32 v117, v212, v213
	global_store_dwordx4 v[118:119], v[114:117], off
	s_nop 1
	v_lshl_add_u64 v[114:115], s[6:7], 0, v[232:233]
	global_store_dwordx2 v[114:115], v[230:231], off
	s_and_saveexec_b64 s[22:23], s[0:1]
	s_cbranch_execz .LBB0_332
	v_lshl_add_u64 v[114:115], v[196:197], 2, s[8:9]
	s_waitcnt lgkmcnt(0)
	v_add_f32_e32 v112, v112, v113
	global_atomic_add_f32 v[114:115], v112, off

; #define PG8_STAGE(bufoff, gbase, voff) do { _Pragma("unroll") for (int _i = 0; _i < 2; ++_i) \
;         __builtin_amdgcn_global_load_lds((const unsigned*)((const char*)(gbase) + (voff)[_i]), (PG8_LAS unsigned*)(lds + (bufoff) + ldsw + _i * 8192), 16, 0, 0); } while (0)
; #define PG8_LDA(dst, b, h) do { _Pragma("unroll") for (int m = 0; m < 4; ++m) { if constexpr (FP8) dst##8[m] = PG8_LD32(lds + PG8_SA(b, h) + aoff + m * 2048); else { _Pragma("unroll") for (int k = 0; k < 2; ++k) dst[m][k] = *(const PG8_LAS bf16x8*)(lds + PG8_SA(b, h) + aoff + m * 2048 + k * 1024); } } } while (0)
; #define PG8_LDB(dst, b, h) do { _Pragma("unroll") for (int n = 0; n < 2; ++n) { if constexpr (FP8) dst##8[n] = PG8_LD32(lds + PG8_SB(b, h) + boff + n * 2048); else { _Pragma("unroll") for (int k = 0; k < 2; ++k) dst[n][k] = *(const PG8_LAS bf16x8*)(lds + PG8_SB(b, h) + boff + n * 2048 + k * 1024); } } } while (0)
; #define PG8_WAIT_V(n) asm volatile("s_waitcnt vmcnt(" #n ")" ::: "memory")
; #define PG8_WAIT_L(n) asm volatile("s_waitcnt lgkmcnt(" #n ")" ::: "memory")
; #define PG8_BAR __builtin_amdgcn_s_barrier()
; template <class Epi, class Sched, bool ALIGN_EPI = false, bool SP2 = false, bool FP8 = false>
; __device__ __forceinline__ void gemm_phase(PG8_LAS unsigned char* lds, const Gemm g, const Sched& S, const Epi& E, int wave_id) {
;     ...
;             PG8_LDB(B0, 0, 0); PG8_LDB(B1, 0, 1); PG8_SCHED; PG8_LDA(At, 0, 0); PG8_STAGE(PG8_SA(1, 1), a1 + hstep, voffA);
;             PG8_WAIT_V(8); PG8_WAIT_L(0); PG8_BAR; PG8_MMA(0, 0, At, B0); PG8_MMA(0, 1, At, B1); PG8_BAR; PG8_SCHED;
;             PG8_LDA(At, 0, 1); PG8_STAGE(PG8_SB(0, 0), b2, voffB); PG8_STAGE(PG8_SB(0, 1), b2 + hstep, voffB); PG8_STAGE(PG8_SA(0, 0), a2, voffA);
;             PG8_WAIT_V(8); PG8_WAIT_L(0); PG8_BAR; PG8_MMA(1, 0, At, B0); PG8_MMA(1, 1, At, B1); PG8_BAR; PG8_SCHED;
;             PG8_LDB(B0, 1, 0); PG8_LDB(B1, 1, 1); PG8_SCHED; PG8_LDA(At, 1, 0); PG8_STAGE(PG8_SA(0, 1), a2 + hstep, voffA);
;             PG8_WAIT_V(8); PG8_WAIT_L(0); PG8_BAR; PG8_MMA(0, 0, At, B0); PG8_MMA(0, 1, At, B1); PG8_BAR; PG8_SCHED;
;     __device__ __forceinline__ void operator()(const f32x4 (&acc)[2][2][4][2], const Unit& u, int wr, int wc, int fr, int fq) const {
;     ...
;             for (int m = 0; m < 4; ++m) rs[ai][m] = __hip_atomic_load(ss + row0 + ai * HALF + m * 16, __ATOMIC_RELAXED, __HIP_MEMORY_SCOPE_AGENT);
.LBB0_419:
	ds_read_b128 v[16:19], v187
	ds_read_b128 v[20:23], v187 offset:1024
	ds_read_b128 v[24:27], v187 offset:2048
	ds_read_b128 v[28:31], v187 offset:3072
	ds_read_b128 v[0:3], v188
	ds_read_b128 v[4:7], v188 offset:1024
	ds_read_b128 v[8:11], v188 offset:2048
	ds_read_b128 v[12:15], v188 offset:3072
	s_add_u32 s34, s30, 0xfffc0080
	s_addc_u32 s35, s31, -1
	s_cmp_eq_u32 s74, 12
	s_cselect_b32 s37, s23, s35
	s_cselect_b32 s36, s66, s34
	s_cselect_b32 s35, s21, s71
	s_cselect_b32 s34, s67, s69
	v_lshl_add_u64 v[216:217], s[30:31], 0, v[168:169]
	s_add_i32 m0, s29, 0xc000
	ds_read_b128 v[176:179], v189
	ds_read_b128 v[180:183], v189 offset:1024
	ds_read_b128 v[192:195], v189 offset:2048
	ds_read_b128 v[196:199], v189 offset:3072
	ds_read_b128 v[200:203], v189 offset:4096
	ds_read_b128 v[204:207], v189 offset:5120
	ds_read_b128 v[208:211], v189 offset:6144
	ds_read_b128 v[212:215], v189 offset:7168
	global_load_lds_dwordx4 v[216:217], off
	v_lshl_add_u64 v[216:217], s[30:31], 0, v[170:171]
	s_add_i32 m0, s29, 0xe000
	s_nop 0
	global_load_lds_dwordx4 v[216:217], off
	s_waitcnt vmcnt(8)
	s_waitcnt lgkmcnt(0)
	s_barrier
	s_waitcnt lgkmcnt(0)
	v_mfma_f32_16x16x128_f8f6f4 v[156:159], v[16:23], v[176:183], v[156:159]
	v_mfma_f32_16x16x128_f8f6f4 v[152:155], v[24:31], v[176:183], v[152:155]
	v_mfma_f32_16x16x128_f8f6f4 v[148:151], v[16:23], v[192:199], v[148:151]
	v_mfma_f32_16x16x128_f8f6f4 v[136:139], v[24:31], v[192:199], v[136:139]
	v_mfma_f32_16x16x128_f8f6f4 v[124:127], v[16:23], v[200:207], v[124:127]
	v_mfma_f32_16x16x128_f8f6f4 v[120:123], v[24:31], v[200:207], v[120:123]
	v_mfma_f32_16x16x128_f8f6f4 v[108:111], v[16:23], v[208:215], v[108:111]
	v_mfma_f32_16x16x128_f8f6f4 v[104:107], v[24:31], v[208:215], v[104:107]
	v_mfma_f32_16x16x128_f8f6f4 v[144:147], v[0:7], v[176:183], v[144:147]
	v_mfma_f32_16x16x128_f8f6f4 v[140:143], v[8:15], v[176:183], v[140:143]
	v_mfma_f32_16x16x128_f8f6f4 v[132:135], v[0:7], v[192:199], v[132:135]
	v_mfma_f32_16x16x128_f8f6f4 v[128:131], v[8:15], v[192:199], v[128:131]
	v_mfma_f32_16x16x128_f8f6f4 v[116:119], v[0:7], v[200:207], v[116:119]
	v_mfma_f32_16x16x128_f8f6f4 v[112:115], v[8:15], v[200:207], v[112:115]
	v_mfma_f32_16x16x128_f8f6f4 v[100:103], v[0:7], v[208:215], v[100:103]
	v_mfma_f32_16x16x128_f8f6f4 v[96:99], v[8:15], v[208:215], v[96:99]
	s_barrier
	s_add_i32 s75, s59, s44
	v_lshl_add_u64 v[176:177], s[34:35], 0, v[162:163]
	s_mov_b32 m0, s75
	ds_read_b128 v[192:195], v189 offset:16384
	ds_read_b128 v[196:199], v189 offset:17408
	ds_read_b128 v[200:203], v189 offset:18432
	ds_read_b128 v[204:207], v189 offset:19456
	ds_read_b128 v[208:211], v189 offset:20480
	ds_read_b128 v[212:215], v189 offset:21504
	ds_read_b128 v[216:219], v189 offset:22528
	ds_read_b128 v[220:223], v189 offset:23552
	global_load_lds_dwordx4 v[176:177], off
	s_add_i32 m0, s75, 0x2000
	s_add_u32 s78, s34, 0x40000
	v_lshl_add_u64 v[178:179], s[34:35], 0, v[166:167]
	s_addc_u32 s79, s35, 0
	s_add_i32 s75, s60, s44
	global_load_lds_dwordx4 v[178:179], off
	v_lshl_add_u64 v[180:181], s[78:79], 0, v[162:163]
	s_mov_b32 m0, s75
	v_lshl_add_u64 v[182:183], s[36:37], 0, v[164:165]
	global_load_lds_dwordx4 v[180:181], off
	v_lshl_add_u64 v[180:181], s[78:79], 0, v[166:167]
	s_add_i32 m0, s75, 0x2000
	s_nop 0
	global_load_lds_dwordx4 v[180:181], off
	v_lshl_add_u64 v[180:181], s[36:37], 0, v[160:161]
	s_mov_b32 m0, s29
	s_nop 0
	global_load_lds_dwordx4 v[180:181], off
	s_mov_b32 m0, s45
	s_nop 0
	global_load_lds_dwordx4 v[182:183], off
	s_waitcnt vmcnt(8)
	s_waitcnt lgkmcnt(0)
	s_barrier
	s_waitcnt lgkmcnt(0)
	v_mfma_f32_16x16x128_f8f6f4 v[92:95], v[16:23], v[192:199], v[92:95]
	v_mfma_f32_16x16x128_f8f6f4 v[88:91], v[24:31], v[192:199], v[88:91]
	v_mfma_f32_16x16x128_f8f6f4 v[76:79], v[16:23], v[200:207], v[76:79]
	v_mfma_f32_16x16x128_f8f6f4 v[72:75], v[24:31], v[200:207], v[72:75]
	v_mfma_f32_16x16x128_f8f6f4 v[60:63], v[16:23], v[208:215], v[60:63]
	v_mfma_f32_16x16x128_f8f6f4 v[56:59], v[24:31], v[208:215], v[56:59]
	v_mfma_f32_16x16x128_f8f6f4 v[44:47], v[16:23], v[216:223], v[44:47]
	v_mfma_f32_16x16x128_f8f6f4 v[40:43], v[24:31], v[216:223], v[40:43]
	v_mfma_f32_16x16x128_f8f6f4 v[84:87], v[0:7], v[192:199], v[84:87]
	v_mfma_f32_16x16x128_f8f6f4 v[80:83], v[8:15], v[192:199], v[80:83]
	v_mfma_f32_16x16x128_f8f6f4 v[68:71], v[0:7], v[200:207], v[68:71]
	v_mfma_f32_16x16x128_f8f6f4 v[64:67], v[8:15], v[200:207], v[64:67]
	v_mfma_f32_16x16x128_f8f6f4 v[52:55], v[0:7], v[208:215], v[52:55]
	v_mfma_f32_16x16x128_f8f6f4 v[48:51], v[8:15], v[208:215], v[48:51]
	v_mfma_f32_16x16x128_f8f6f4 v[36:39], v[0:7], v[216:223], v[36:39]
	v_mfma_f32_16x16x128_f8f6f4 v[32:35], v[8:15], v[216:223], v[32:35]
	s_barrier
	s_add_i32 s75, 0, 0x18000
	s_add_i32 s78, 0, 0x1c000
	v_add_u32_e32 v12, s75, v185
	v_add_u32_e32 v28, s78, v185
	ds_read_b128 v[0:3], v12
	ds_read_b128 v[4:7], v12 offset:1024
	ds_read_b128 v[8:11], v12 offset:2048
	ds_read_b128 v[12:15], v12 offset:3072
	ds_read_b128 v[16:19], v28
	ds_read_b128 v[20:23], v28 offset:1024
	ds_read_b128 v[24:27], v28 offset:2048
	ds_read_b128 v[28:31], v28 offset:3072
	s_add_u32 s36, s36, 0x40000
	s_addc_u32 s37, s37, 0
	s_mov_b32 m0, s52
	v_lshl_add_u64 v[224:225], s[36:37], 0, v[160:161]
	ds_read_b128 v[192:195], v189 offset:32768
	ds_read_b128 v[196:199], v189 offset:33792
	ds_read_b128 v[200:203], v189 offset:34816
	ds_read_b128 v[204:207], v189 offset:35840
	ds_read_b128 v[208:211], v189 offset:36864
	ds_read_b128 v[212:215], v189 offset:37888
	ds_read_b128 v[216:219], v189 offset:38912
	ds_read_b128 v[220:223], v189 offset:39936
	global_load_lds_dwordx4 v[224:225], off
	v_lshl_add_u64 v[224:225], s[36:37], 0, v[164:165]
	s_mov_b32 m0, s53
	s_nop 0
	global_load_lds_dwordx4 v[224:225], off
	s_waitcnt vmcnt(8)
	s_waitcnt lgkmcnt(0)
	s_barrier
; #define PG8_STAGE(bufoff, gbase, voff) do { _Pragma("unroll") for (int _i = 0; _i < 2; ++_i) \
;         __builtin_amdgcn_global_load_lds((const unsigned*)((const char*)(gbase) + (voff)[_i]), (PG8_LAS unsigned*)(lds + (bufoff) + ldsw + _i * 8192), 16, 0, 0); } while (0)
; #define PG8_LDA(dst, b, h) do { _Pragma("unroll") for (int m = 0; m < 4; ++m) { if constexpr (FP8) dst##8[m] = PG8_LD32(lds + PG8_SA(b, h) + aoff + m * 2048); else { _Pragma("unroll") for (int k = 0; k < 2; ++k) dst[m][k] = *(const PG8_LAS bf16x8*)(lds + PG8_SA(b, h) + aoff + m * 2048 + k * 1024); } } } while (0)
; #define PG8_WAIT_V(n) asm volatile("s_waitcnt vmcnt(" #n ")" ::: "memory")
; #define PG8_WAIT_L(n) asm volatile("s_waitcnt lgkmcnt(" #n ")" ::: "memory")
; #define PG8_BAR __builtin_amdgcn_s_barrier()
; #define PG8_SCHED __builtin_amdgcn_sched_barrier(0)
; template <class Epi, class Sched, bool ALIGN_EPI = false, bool SP2 = false, bool FP8 = false>
; __device__ __forceinline__ void gemm_phase(PG8_LAS unsigned char* lds, const Gemm g, const Sched& S, const Epi& E, int wave_id) {
;     ...
;             PG8_WAIT_V(8); PG8_WAIT_L(0); PG8_BAR; PG8_MMA(0, 0, At, B0); PG8_MMA(0, 1, At, B1); PG8_BAR; PG8_SCHED;
;             PG8_LDA(At, 1, 1); PG8_STAGE(PG8_SB(1, 0), b3, voffB); PG8_STAGE(PG8_SB(1, 1), b3 + hstep, voffB); PG8_STAGE(PG8_SA(1, 0), a3, voffA);
;             PG8_WAIT_V(8); PG8_WAIT_L(0); PG8_BAR; PG8_MMA(1, 0, At, B0); PG8_MMA(1, 1, At, B1); PG8_BAR; PG8_SCHED;
;     __device__ __forceinline__ void operator()(const f32x4 (&acc)[2][2][4][2], const Unit& u, int wr, int wc, int fr, int fq) const {
;         const int row0 = u.pm * BM + wr * 64 + fr, col0 = u.pn * BM + wc * 32 + 8 * fq;
;         float rs[2][4];
; #pragma unroll
;         for (int ai = 0; ai < 2; ++ai)
; #pragma unroll
;             for (int m = 0; m < 4; ++m) rs[ai][m] = __hip_atomic_load(ss + row0 + ai * HALF + m * 16, __ATOMIC_RELAXED, __HIP_MEMORY_SCOPE_AGENT);
;         asm volatile("" ::: "memory");
	s_waitcnt lgkmcnt(0)
	v_mfma_f32_16x16x128_f8f6f4 v[156:159], v[0:7], v[192:199], v[156:159]
	v_mfma_f32_16x16x128_f8f6f4 v[152:155], v[8:15], v[192:199], v[152:155]
	v_mfma_f32_16x16x128_f8f6f4 v[148:151], v[0:7], v[200:207], v[148:151]
	v_mfma_f32_16x16x128_f8f6f4 v[136:139], v[8:15], v[200:207], v[136:139]
	v_mfma_f32_16x16x128_f8f6f4 v[124:127], v[0:7], v[208:215], v[124:127]
	v_mfma_f32_16x16x128_f8f6f4 v[120:123], v[8:15], v[208:215], v[120:123]
	v_mfma_f32_16x16x128_f8f6f4 v[108:111], v[0:7], v[216:223], v[108:111]
	v_mfma_f32_16x16x128_f8f6f4 v[104:107], v[8:15], v[216:223], v[104:107]
	v_mfma_f32_16x16x128_f8f6f4 v[144:147], v[16:23], v[192:199], v[144:147]
	v_mfma_f32_16x16x128_f8f6f4 v[140:143], v[24:31], v[192:199], v[140:143]
	v_mfma_f32_16x16x128_f8f6f4 v[132:135], v[16:23], v[200:207], v[132:135]
	v_mfma_f32_16x16x128_f8f6f4 v[128:131], v[24:31], v[200:207], v[128:131]
	v_mfma_f32_16x16x128_f8f6f4 v[116:119], v[16:23], v[208:215], v[116:119]
	v_mfma_f32_16x16x128_f8f6f4 v[112:115], v[24:31], v[208:215], v[112:115]
	v_mfma_f32_16x16x128_f8f6f4 v[100:103], v[16:23], v[216:223], v[100:103]
	v_mfma_f32_16x16x128_f8f6f4 v[96:99], v[24:31], v[216:223], v[96:99]
	s_barrier
	s_add_i32 s36, s75, s44
	v_lshl_add_u64 v[176:177], v[176:177], 0, s[10:11]
	s_mov_b32 m0, s36
	ds_read_b128 v[192:195], v189 offset:49152
	ds_read_b128 v[196:199], v189 offset:50176
	ds_read_b128 v[200:203], v189 offset:51200
	ds_read_b128 v[204:207], v189 offset:52224
	ds_read_b128 v[208:211], v189 offset:53248
	ds_read_b128 v[212:215], v189 offset:54272
	ds_read_b128 v[216:219], v189 offset:55296
	ds_read_b128 v[220:223], v189 offset:56320
	global_load_lds_dwordx4 v[176:177], off
	s_add_i32 m0, s36, 0x2000
	s_add_u32 s34, s34, 0x40080
	v_lshl_add_u64 v[176:177], v[178:179], 0, s[10:11]
	s_addc_u32 s35, s35, 0
	s_add_i32 s36, s78, s44
	global_load_lds_dwordx4 v[176:177], off
	v_lshl_add_u64 v[176:177], s[34:35], 0, v[162:163]
	s_mov_b32 m0, s36
	s_nop 0
	global_load_lds_dwordx4 v[176:177], off
	v_lshl_add_u64 v[176:177], s[34:35], 0, v[166:167]
	s_add_i32 m0, s36, 0x2000
	s_nop 0
	global_load_lds_dwordx4 v[176:177], off
	v_lshl_add_u64 v[176:177], v[180:181], 0, s[10:11]
	s_mov_b32 m0, s55
	s_nop 0
	global_load_lds_dwordx4 v[176:177], off
	v_lshl_add_u64 v[176:177], v[182:183], 0, s[10:11]
	s_mov_b32 m0, s56
	s_nop 0
	global_load_lds_dwordx4 v[176:177], off
	s_waitcnt vmcnt(8)
	s_waitcnt lgkmcnt(0)
	s_barrier
	s_waitcnt lgkmcnt(0)
	v_mfma_f32_16x16x128_f8f6f4 v[92:95], v[0:7], v[192:199], v[92:95]
	v_mfma_f32_16x16x128_f8f6f4 v[88:91], v[8:15], v[192:199], v[88:91]
	v_mfma_f32_16x16x128_f8f6f4 v[76:79], v[0:7], v[200:207], v[76:79]
	v_mfma_f32_16x16x128_f8f6f4 v[72:75], v[8:15], v[200:207], v[72:75]
	v_mfma_f32_16x16x128_f8f6f4 v[60:63], v[0:7], v[208:215], v[60:63]
	v_mfma_f32_16x16x128_f8f6f4 v[56:59], v[8:15], v[208:215], v[56:59]
	v_mfma_f32_16x16x128_f8f6f4 v[44:47], v[0:7], v[216:223], v[44:47]
	v_mfma_f32_16x16x128_f8f6f4 v[40:43], v[8:15], v[216:223], v[40:43]
	v_mfma_f32_16x16x128_f8f6f4 v[84:87], v[16:23], v[192:199], v[84:87]
	v_mfma_f32_16x16x128_f8f6f4 v[80:83], v[24:31], v[192:199], v[80:83]
	v_mfma_f32_16x16x128_f8f6f4 v[68:71], v[16:23], v[200:207], v[68:71]
	v_mfma_f32_16x16x128_f8f6f4 v[64:67], v[24:31], v[200:207], v[64:67]
	v_mfma_f32_16x16x128_f8f6f4 v[52:55], v[16:23], v[208:215], v[52:55]
	v_mfma_f32_16x16x128_f8f6f4 v[48:51], v[24:31], v[208:215], v[48:51]
	v_mfma_f32_16x16x128_f8f6f4 v[36:39], v[16:23], v[216:223], v[36:39]
	v_mfma_f32_16x16x128_f8f6f4 v[32:35], v[24:31], v[216:223], v[32:35]
	s_barrier
	s_add_i32 s74, s74, 2
	s_add_u32 s30, s30, 0x100
	s_addc_u32 s31, s31, 0
	s_add_u32 s69, s69, 0x100
	s_addc_u32 s71, s71, 0
	s_cmp_gt_u32 s74, 13
	s_cbranch_scc0 .LBB0_419
	v_lshl_add_u32 v4, s28, 8, v184
	v_ashrrev_i32_e32 v5, 31, v4
	s_nop 15
	s_nop 15
	v_lshl_add_u64 v[0:1], v[4:5], 2, s[8:9]
	global_load_dword v7, v[0:1], off sc1
	global_load_dword v16, v[0:1], off offset:64 sc1
	v_lshlrev_b64 v[14:15], 13, v[4:5]
	global_load_dword v176, v[0:1], off offset:128 sc1
	global_load_dword v177, v[0:1], off offset:192 sc1
	global_load_dword v178, v[0:1], off offset:512 sc1
	global_load_dword v179, v[0:1], off offset:576 sc1
	global_load_dword v6, v[0:1], off offset:640 sc1
	global_load_dword v5, v[0:1], off offset:704 sc1
	v_lshl_add_u64 v[0:1], s[40:41], 0, v[14:15]
	v_mov_b32_e32 v8, 0
	v_mov_b32_e32 v9, 0
	v_mov_b32_e32 v10, 0
	v_mov_b32_e32 v11, 0
	v_lshl_or_b32 v2, s65, 8, v186
	v_ashrrev_i32_e32 v3, 31, v2
	v_lshl_add_u64 v[0:1], v[0:1], 0, v[2:3]
	v_or_b32_e32 v12, 16, v4
	v_ashrrev_i32_e32 v13, 31, v12
	v_lshlrev_b64 v[12:13], 13, v[12:13]
	s_mov_b32 s65, s20
	s_mov_b32 s28, s22
	s_mov_b64 s[34:35], s[26:27]
	s_mov_b64 s[30:31], s[24:25]
	s_waitcnt vmcnt(0)
;     __device__ __forceinline__ void operator()(const f32x4 (&acc)[2][2][4][2], const Unit& u, int wr, int wc, int fr, int fq) const {
;     ...
;         for (int ai = 0; ai < 2; ++ai)
; #pragma unroll
;             for (int m = 0; m < 4; ++m) {
;                 const int row = row0 + ai * HALF + m * 16;
;                 const float rstd = __builtin_amdgcn_rsqf(rs[ai][m] * (1.f / DM) + EPS) * (1.f / W1_SCALE);
; #pragma unroll
;                 for (int bj = 0; bj < 2; ++bj) {
;                     f32x4 v0 = acc[ai][bj][m][0] * rstd, v1 = acc[ai][bj][m][1] * rstd;
; #pragma unroll
;                     for (int e = 0; e < 4; ++e) { const float a = fmaxf(v0[e], 0.f), b = fmaxf(v1[e], 0.f); v0[e] = fminf(a * a, 448.f); v1[e] = fminf(b * b, 448.f); }
;                     int w0 = __builtin_amdgcn_cvt_pk_fp8_f32(v0[0], v0[1], 0, false); w0 = __builtin_amdgcn_cvt_pk_fp8_f32(v0[2], v0[3], w0, true);
;                     int w1 = __builtin_amdgcn_cvt_pk_fp8_f32(v1[0], v1[1], 0, false); w1 = __builtin_amdgcn_cvt_pk_fp8_f32(v1[2], v1[3], w1, true);
;                     *(v2u*)(O + (size_t)row * FF + col0 + bj * HALF) = (v2u){(unsigned)w0, (unsigned)w1};
	v_fmamk_f32 v7, v7, 0x3a000000, v190
	v_fmamk_f32 v14, v16, 0x3a000000, v190
	v_rsq_f32_e32 v7, v7
	v_rsq_f32_e32 v15, v14
	v_mul_f32_e32 v14, 0x3d000000, v7
	v_mul_f32_e32 v16, 0x3d000000, v15
	v_pk_mul_f32 v[20:21], v[156:157], v[14:15] op_sel_hi:[1,0]
	v_pk_mul_f32 v[24:25], v[152:153], v[14:15] op_sel_hi:[1,0]
	v_pk_mul_f32 v[18:19], v[158:159], v[14:15] op_sel_hi:[1,0]
	v_pk_mul_f32 v[22:23], v[154:155], v[14:15] op_sel_hi:[1,0]
	v_pk_mul_f32 v[26:27], v[146:147], v[14:15] op_sel_hi:[1,0]
	v_pk_mul_f32 v[28:29], v[144:145], v[14:15] op_sel_hi:[1,0]
	v_pk_mul_f32 v[30:31], v[142:143], v[14:15] op_sel_hi:[1,0]
	v_pk_mul_f32 v[14:15], v[140:141], v[14:15] op_sel_hi:[1,0]
	v_pk_mul_f32 v[140:141], v[150:151], v[16:17] op_sel_hi:[1,0]
	v_pk_mul_f32 v[142:143], v[148:149], v[16:17] op_sel_hi:[1,0]
	v_pk_mul_f32 v[138:139], v[138:139], v[16:17] op_sel_hi:[1,0]
	v_max_f32_e32 v7, 0, v20
	v_max_f32_e32 v17, 0, v24
	v_max_f32_e32 v20, 0, v21
	v_max_f32_e32 v21, 0, v25
	v_max_f32_e32 v24, 0, v28
	v_max_f32_e32 v14, 0, v14
	v_max_f32_e32 v25, 0, v29
	v_max_f32_e32 v15, 0, v15
	v_mul_f32_e32 v7, v7, v7
	v_mul_f32_e32 v17, v17, v17
	v_mul_f32_e32 v20, v20, v20
	v_mul_f32_e32 v21, v21, v21
	v_mul_f32_e32 v24, v24, v24
	v_mul_f32_e32 v14, v14, v14
	v_mul_f32_e32 v25, v25, v25
	v_mul_f32_e32 v15, v15, v15
	v_min_f32_e32 v7, 0x43e00000, v7
	v_min_f32_e32 v17, 0x43e00000, v17
	v_min_f32_e32 v20, 0x43e00000, v20
	v_min_f32_e32 v21, 0x43e00000, v21
	v_min_f32_e32 v24, 0x43e00000, v24
	v_min_f32_e32 v14, 0x43e00000, v14
	v_min_f32_e32 v25, 0x43e00000, v25
	v_min_f32_e32 v15, 0x43e00000, v15
	v_cvt_pk_fp8_f32 v8, v7, v20
	v_cvt_pk_fp8_f32 v9, v17, v21
	v_max_f32_e32 v18, 0, v18
	v_max_f32_e32 v22, 0, v22
	v_max_f32_e32 v19, 0, v19
	v_max_f32_e32 v23, 0, v23
	v_cvt_pk_fp8_f32 v10, v24, v25
	v_cvt_pk_fp8_f32 v11, v14, v15
	v_max_f32_e32 v26, 0, v26
	v_max_f32_e32 v28, 0, v30
	v_max_f32_e32 v27, 0, v27
	v_max_f32_e32 v29, 0, v31
	v_mul_f32_e32 v18, v18, v18
	v_mul_f32_e32 v22, v22, v22
	v_mul_f32_e32 v19, v19, v19
	v_mul_f32_e32 v23, v23, v23
	v_mul_f32_e32 v26, v26, v26
	v_mul_f32_e32 v28, v28, v28
	v_mul_f32_e32 v27, v27, v27
	v_mul_f32_e32 v29, v29, v29
	v_min_f32_e32 v18, 0x43e00000, v18
	v_min_f32_e32 v22, 0x43e00000, v22
	v_min_f32_e32 v19, 0x43e00000, v19
	v_min_f32_e32 v23, 0x43e00000, v23
	v_min_f32_e32 v26, 0x43e00000, v26
	v_min_f32_e32 v28, 0x43e00000, v28
	v_min_f32_e32 v27, 0x43e00000, v27
	v_min_f32_e32 v29, 0x43e00000, v29
	v_cvt_pk_fp8_f32 v8, v18, v19 op_sel:[0,0,1]
	v_cvt_pk_fp8_f32 v9, v22, v23 op_sel:[0,0,1]
	v_cvt_pk_fp8_f32 v10, v26, v27 op_sel:[0,0,1]
	v_cvt_pk_fp8_f32 v11, v28, v29 op_sel:[0,0,1]
	v_pk_mul_f32 v[14:15], v[136:137], v[16:17] op_sel_hi:[1,0]
	global_store_dwordx2 v[0:1], v[8:9], off
	global_store_dwordx2 v[0:1], v[10:11], off offset:128
	v_max_f32_e32 v8, 0, v14
	v_mul_f32_e32 v8, v8, v8
	v_min_f32_e32 v10, 0x43e00000, v8
	v_max_f32_e32 v8, 0, v143
	v_max_f32_e32 v9, 0, v15
	v_mul_f32_e32 v8, v8, v8
	v_min_f32_e32 v11, 0x43e00000, v8
	v_mul_f32_e32 v8, v9, v9
	v_min_f32_e32 v14, 0x43e00000, v8
	v_max_f32_e32 v8, 0, v140
	v_max_f32_e32 v9, 0, v138
	v_mul_f32_e32 v8, v8, v8
	v_min_f32_e32 v15, 0x43e00000, v8
	v_mul_f32_e32 v8, v9, v9
	v_max_f32_e32 v7, 0, v142
	v_min_f32_e32 v17, 0x43e00000, v8
	v_max_f32_e32 v8, 0, v141
	v_mul_f32_e32 v7, v7, v7
	v_mul_f32_e32 v8, v8, v8
	v_min_f32_e32 v7, 0x43e00000, v7
	v_min_f32_e32 v19, 0x43e00000, v8
	v_mov_b32_e32 v8, 0
	v_mov_b32_e32 v9, 0
	v_cvt_pk_fp8_f32 v8, v7, v11
	v_cvt_pk_fp8_f32 v9, v10, v14
	v_max_f32_e32 v18, 0, v139
	v_mul_f32_e32 v7, v18, v18
	v_min_f32_e32 v7, 0x43e00000, v7
	v_lshl_add_u64 v[10:11], s[40:41], 0, v[12:13]
	v_pk_mul_f32 v[12:13], v[134:135], v[16:17] op_sel_hi:[1,0]
	v_cvt_pk_fp8_f32 v8, v15, v19 op_sel:[0,0,1]
	v_cvt_pk_fp8_f32 v9, v17, v7 op_sel:[0,0,1]
	v_pk_mul_f32 v[14:15], v[132:133], v[16:17] op_sel_hi:[1,0]
	v_pk_mul_f32 v[18:19], v[130:131], v[16:17] op_sel_hi:[1,0]
	v_pk_mul_f32 v[16:17], v[128:129], v[16:17] op_sel_hi:[1,0]
	v_max_f32_e32 v12, 0, v12
	v_max_f32_e32 v7, 0, v14
	v_max_f32_e32 v14, 0, v16
	v_max_f32_e32 v16, 0, v17
	v_max_f32_e32 v17, 0, v18
	v_mul_f32_e32 v12, v12, v12
	v_mul_f32_e32 v14, v14, v14
	v_mul_f32_e32 v16, v16, v16
	v_min_f32_e32 v18, 0x43e00000, v12
	v_mul_f32_e32 v12, v17, v17
	v_min_f32_e32 v14, 0x43e00000, v14
	v_max_f32_e32 v15, 0, v15
	v_min_f32_e32 v16, 0x43e00000, v16
	v_min_f32_e32 v17, 0x43e00000, v12
	v_max_f32_e32 v12, 0, v13
	v_mov_b32_e32 v13, 0
	v_mul_f32_e32 v7, v7, v7
	v_mul_f32_e32 v15, v15, v15
	v_mul_f32_e32 v12, v12, v12
	v_cvt_pk_fp8_f32 v13, v14, v16
	v_min_f32_e32 v7, 0x43e00000, v7
	v_min_f32_e32 v15, 0x43e00000, v15
	v_max_f32_e32 v19, 0, v19
	v_min_f32_e32 v20, 0x43e00000, v12
	v_mov_b32_e32 v12, 0
	v_cvt_pk_fp8_f32 v12, v7, v15
	v_mul_f32_e32 v7, v19, v19
	v_min_f32_e32 v7, 0x43e00000, v7
	v_cvt_pk_fp8_f32 v13, v17, v7 op_sel:[0,0,1]
	v_fmamk_f32 v7, v176, 0x3a000000, v190
	v_rsq_f32_e32 v7, v7
	v_cvt_pk_fp8_f32 v12, v18, v20 op_sel:[0,0,1]
	v_lshl_add_u64 v[10:11], v[10:11], 0, v[2:3]
	global_store_dwordx2 v[10:11], v[8:9], off
	global_store_dwordx2 v[10:11], v[12:13], off offset:128
	v_mul_f32_e32 v10, 0x3d000000, v7
	v_pk_mul_f32 v[12:13], v[126:127], v[10:11] op_sel_hi:[1,0]
	v_pk_mul_f32 v[16:17], v[122:123], v[10:11] op_sel_hi:[1,0]
	v_max_f32_e32 v12, 0, v12
	v_pk_mul_f32 v[18:19], v[120:121], v[10:11] op_sel_hi:[1,0]
	v_max_f32_e32 v16, 0, v16
	v_mul_f32_e32 v12, v12, v12
	v_pk_mul_f32 v[14:15], v[124:125], v[10:11] op_sel_hi:[1,0]
	v_max_f32_e32 v11, 0, v18
	v_min_f32_e32 v18, 0x43e00000, v12
	v_mul_f32_e32 v12, v16, v16
	v_max_f32_e32 v7, 0, v14
	v_max_f32_e32 v14, 0, v15
;     __device__ __forceinline__ void operator()(const f32x4 (&acc)[2][2][4][2], const Unit& u, int wr, int wc, int fr, int fq) const {
;     ...
;         for (int ai = 0; ai < 2; ++ai)
; #pragma unroll
;             for (int m = 0; m < 4; ++m) {
;                 const int row = row0 + ai * HALF + m * 16;
;                 const float rstd = __builtin_amdgcn_rsqf(rs[ai][m] * (1.f / DM) + EPS) * (1.f / W1_SCALE);
; #pragma unroll
;                 for (int bj = 0; bj < 2; ++bj) {
;                     f32x4 v0 = acc[ai][bj][m][0] * rstd, v1 = acc[ai][bj][m][1] * rstd;
; #pragma unroll
;                     for (int e = 0; e < 4; ++e) { const float a = fmaxf(v0[e], 0.f), b = fmaxf(v1[e], 0.f); v0[e] = fminf(a * a, 448.f); v1[e] = fminf(b * b, 448.f); }
;                     int w0 = __builtin_amdgcn_cvt_pk_fp8_f32(v0[0], v0[1], 0, false); w0 = __builtin_amdgcn_cvt_pk_fp8_f32(v0[2], v0[3], w0, true);
;                     int w1 = __builtin_amdgcn_cvt_pk_fp8_f32(v1[0], v1[1], 0, false); w1 = __builtin_amdgcn_cvt_pk_fp8_f32(v1[2], v1[3], w1, true);
;                     *(v2u*)(O + (size_t)row * FF + col0 + bj * HALF) = (v2u){(unsigned)w0, (unsigned)w1};
	v_max_f32_e32 v15, 0, v19
	v_min_f32_e32 v16, 0x43e00000, v12
	v_max_f32_e32 v12, 0, v13
	v_mul_f32_e32 v7, v7, v7
	v_mul_f32_e32 v11, v11, v11
	v_mul_f32_e32 v14, v14, v14
	v_mul_f32_e32 v15, v15, v15
	v_mul_f32_e32 v12, v12, v12
	v_min_f32_e32 v7, 0x43e00000, v7
	v_min_f32_e32 v11, 0x43e00000, v11
	v_min_f32_e32 v14, 0x43e00000, v14
	v_min_f32_e32 v15, 0x43e00000, v15
	v_min_f32_e32 v19, 0x43e00000, v12
	v_mov_b32_e32 v12, 0
	v_mov_b32_e32 v13, 0
	v_cvt_pk_fp8_f32 v12, v7, v14
	v_cvt_pk_fp8_f32 v13, v11, v15
	v_max_f32_e32 v17, 0, v17
	v_mul_f32_e32 v7, v17, v17
	v_min_f32_e32 v7, 0x43e00000, v7
	v_cvt_pk_fp8_f32 v12, v18, v19 op_sel:[0,0,1]
	v_cvt_pk_fp8_f32 v13, v16, v7 op_sel:[0,0,1]
	v_pk_mul_f32 v[14:15], v[118:119], v[10:11] op_sel_hi:[1,0]
	v_pk_mul_f32 v[16:17], v[116:117], v[10:11] op_sel_hi:[1,0]
	v_pk_mul_f32 v[18:19], v[114:115], v[10:11] op_sel_hi:[1,0]
	v_pk_mul_f32 v[10:11], v[112:113], v[10:11] op_sel_hi:[1,0]
	v_max_f32_e32 v7, 0, v16
	v_max_f32_e32 v10, 0, v10
	v_mul_f32_e32 v10, v10, v10
	v_min_f32_e32 v16, 0x43e00000, v10
	v_max_f32_e32 v10, 0, v17
	v_max_f32_e32 v11, 0, v11
	v_mul_f32_e32 v10, v10, v10
	v_min_f32_e32 v17, 0x43e00000, v10
	v_mul_f32_e32 v10, v11, v11
	v_min_f32_e32 v20, 0x43e00000, v10
	v_max_f32_e32 v10, 0, v14
	v_max_f32_e32 v11, 0, v18
	v_mul_f32_e32 v10, v10, v10
	v_min_f32_e32 v14, 0x43e00000, v10
	v_mul_f32_e32 v10, v11, v11
	v_min_f32_e32 v18, 0x43e00000, v10
	v_max_f32_e32 v10, 0, v15
	v_mov_b32_e32 v11, 0
	v_mul_f32_e32 v7, v7, v7
	v_mul_f32_e32 v10, v10, v10
	v_cvt_pk_fp8_f32 v11, v16, v20
	v_min_f32_e32 v7, 0x43e00000, v7
	v_max_f32_e32 v15, 0, v19
	v_min_f32_e32 v19, 0x43e00000, v10
	v_mov_b32_e32 v10, 0
	v_cvt_pk_fp8_f32 v10, v7, v17
	v_mul_f32_e32 v7, v15, v15
	v_min_f32_e32 v7, 0x43e00000, v7
	v_or_b32_e32 v8, 32, v4
	v_cvt_pk_fp8_f32 v11, v18, v7 op_sel:[0,0,1]
	v_fmamk_f32 v7, v177, 0x3a000000, v190
	v_ashrrev_i32_e32 v9, 31, v8
	v_rsq_f32_e32 v7, v7
	v_lshlrev_b64 v[8:9], 13, v[8:9]
	v_cvt_pk_fp8_f32 v10, v14, v19 op_sel:[0,0,1]
	v_lshl_add_u64 v[8:9], s[40:41], 0, v[8:9]
	v_lshl_add_u64 v[8:9], v[8:9], 0, v[2:3]
	global_store_dwordx2 v[8:9], v[12:13], off
	global_store_dwordx2 v[8:9], v[10:11], off offset:128
	v_or_b32_e32 v8, 48, v4
	v_mul_f32_e32 v4, 0x3d000000, v7
	v_pk_mul_f32 v[10:11], v[110:111], v[4:5] op_sel_hi:[1,0]
	v_pk_mul_f32 v[14:15], v[106:107], v[4:5] op_sel_hi:[1,0]
	v_max_f32_e32 v10, 0, v10
	v_pk_mul_f32 v[12:13], v[108:109], v[4:5] op_sel_hi:[1,0]
	v_pk_mul_f32 v[16:17], v[104:105], v[4:5] op_sel_hi:[1,0]
	v_max_f32_e32 v14, 0, v14
	v_mul_f32_e32 v10, v10, v10
	v_max_f32_e32 v7, 0, v12
	v_max_f32_e32 v12, 0, v16
	v_max_f32_e32 v16, 0, v17
	v_min_f32_e32 v17, 0x43e00000, v10
	v_mul_f32_e32 v10, v14, v14
	v_max_f32_e32 v13, 0, v13
	v_min_f32_e32 v14, 0x43e00000, v10
	v_max_f32_e32 v10, 0, v11
	v_mul_f32_e32 v7, v7, v7
	v_mul_f32_e32 v12, v12, v12
	v_mul_f32_e32 v13, v13, v13
	v_mul_f32_e32 v16, v16, v16
	v_mul_f32_e32 v10, v10, v10
	v_min_f32_e32 v7, 0x43e00000, v7
	v_min_f32_e32 v12, 0x43e00000, v12
	v_min_f32_e32 v13, 0x43e00000, v13
	v_min_f32_e32 v16, 0x43e00000, v16
	v_min_f32_e32 v18, 0x43e00000, v10
	v_mov_b32_e32 v10, 0
	v_mov_b32_e32 v11, 0
	v_cvt_pk_fp8_f32 v10, v7, v13
	v_cvt_pk_fp8_f32 v11, v12, v16
	v_max_f32_e32 v15, 0, v15
	v_mul_f32_e32 v7, v15, v15
	v_min_f32_e32 v7, 0x43e00000, v7
	v_pk_mul_f32 v[12:13], v[102:103], v[4:5] op_sel_hi:[1,0]
	v_cvt_pk_fp8_f32 v10, v17, v18 op_sel:[0,0,1]
	v_cvt_pk_fp8_f32 v11, v14, v7 op_sel:[0,0,1]
	v_pk_mul_f32 v[14:15], v[100:101], v[4:5] op_sel_hi:[1,0]
	v_pk_mul_f32 v[16:17], v[98:99], v[4:5] op_sel_hi:[1,0]
	v_pk_mul_f32 v[18:19], v[96:97], v[4:5] op_sel_hi:[1,0]
	v_max_f32_e32 v12, 0, v12
	v_max_f32_e32 v4, 0, v14
	v_max_f32_e32 v7, 0, v18
	v_max_f32_e32 v14, 0, v15
	v_max_f32_e32 v15, 0, v19
	v_max_f32_e32 v16, 0, v16
	v_mul_f32_e32 v12, v12, v12
	v_mul_f32_e32 v7, v7, v7
	v_mul_f32_e32 v15, v15, v15
	v_min_f32_e32 v18, 0x43e00000, v12
	v_mul_f32_e32 v12, v16, v16
	v_min_f32_e32 v7, 0x43e00000, v7
	v_min_f32_e32 v15, 0x43e00000, v15
	v_min_f32_e32 v16, 0x43e00000, v12
	v_max_f32_e32 v12, 0, v13
	v_mov_b32_e32 v13, 0
	v_mul_f32_e32 v4, v4, v4
	v_mul_f32_e32 v14, v14, v14
	v_mul_f32_e32 v12, v12, v12
	v_cvt_pk_fp8_f32 v13, v7, v15
	v_min_f32_e32 v4, 0x43e00000, v4
	v_min_f32_e32 v14, 0x43e00000, v14
	v_max_f32_e32 v17, 0, v17
	v_min_f32_e32 v19, 0x43e00000, v12
	v_mov_b32_e32 v12, 0
	v_cvt_pk_fp8_f32 v12, v4, v14
	v_mul_f32_e32 v4, v17, v17
	v_min_f32_e32 v4, 0x43e00000, v4
	v_cvt_pk_fp8_f32 v13, v16, v4 op_sel:[0,0,1]
	v_fmamk_f32 v4, v178, 0x3a000000, v190
	v_ashrrev_i32_e32 v9, 31, v8
	v_rsq_f32_e32 v4, v4
	v_lshlrev_b64 v[8:9], 13, v[8:9]
	v_cvt_pk_fp8_f32 v12, v18, v19 op_sel:[0,0,1]
	v_lshl_add_u64 v[8:9], s[40:41], 0, v[8:9]
	v_lshl_add_u64 v[2:3], v[8:9], 0, v[2:3]
	global_store_dwordx2 v[2:3], v[10:11], off
	global_store_dwordx2 v[2:3], v[12:13], off offset:128
	v_mul_f32_e32 v2, 0x3d000000, v4
	v_pk_mul_f32 v[8:9], v[94:95], v[2:3] op_sel_hi:[1,0]
	v_pk_mul_f32 v[10:11], v[92:93], v[2:3] op_sel_hi:[1,0]
	v_pk_mul_f32 v[12:13], v[90:91], v[2:3] op_sel_hi:[1,0]
	v_max_f32_e32 v8, 0, v8
	v_max_f32_e32 v7, 0, v11
	v_max_f32_e32 v11, 0, v12
	v_mul_f32_e32 v8, v8, v8
	v_pk_mul_f32 v[14:15], v[88:89], v[2:3] op_sel_hi:[1,0]
	v_min_f32_e32 v12, 0x43e00000, v8
	v_mul_f32_e32 v8, v11, v11
	v_max_f32_e32 v3, 0, v10
	v_max_f32_e32 v4, 0, v14
	v_max_f32_e32 v10, 0, v15
	v_min_f32_e32 v11, 0x43e00000, v8
	v_max_f32_e32 v8, 0, v9
	v_mul_f32_e32 v3, v3, v3
	v_mul_f32_e32 v4, v4, v4
	v_mul_f32_e32 v7, v7, v7
	v_mul_f32_e32 v10, v10, v10
	v_mul_f32_e32 v8, v8, v8
	v_min_f32_e32 v3, 0x43e00000, v3
;     __device__ __forceinline__ void operator()(const f32x4 (&acc)[2][2][4][2], const Unit& u, int wr, int wc, int fr, int fq) const {
;     ...
;         for (int ai = 0; ai < 2; ++ai)
; #pragma unroll
;             for (int m = 0; m < 4; ++m) {
;                 const int row = row0 + ai * HALF + m * 16;
;                 const float rstd = __builtin_amdgcn_rsqf(rs[ai][m] * (1.f / DM) + EPS) * (1.f / W1_SCALE);
; #pragma unroll
;                 for (int bj = 0; bj < 2; ++bj) {
;                     f32x4 v0 = acc[ai][bj][m][0] * rstd, v1 = acc[ai][bj][m][1] * rstd;
; #pragma unroll
;                     for (int e = 0; e < 4; ++e) { const float a = fmaxf(v0[e], 0.f), b = fmaxf(v1[e], 0.f); v0[e] = fminf(a * a, 448.f); v1[e] = fminf(b * b, 448.f); }
;                     int w0 = __builtin_amdgcn_cvt_pk_fp8_f32(v0[0], v0[1], 0, false); w0 = __builtin_amdgcn_cvt_pk_fp8_f32(v0[2], v0[3], w0, true);
;                     int w1 = __builtin_amdgcn_cvt_pk_fp8_f32(v1[0], v1[1], 0, false); w1 = __builtin_amdgcn_cvt_pk_fp8_f32(v1[2], v1[3], w1, true);
;                     *(v2u*)(O + (size_t)row * FF + col0 + bj * HALF) = (v2u){(unsigned)w0, (unsigned)w1};
	v_min_f32_e32 v4, 0x43e00000, v4
	v_min_f32_e32 v7, 0x43e00000, v7
	v_min_f32_e32 v10, 0x43e00000, v10
	v_min_f32_e32 v14, 0x43e00000, v8
	v_mov_b32_e32 v8, 0
	v_mov_b32_e32 v9, 0
	v_cvt_pk_fp8_f32 v8, v3, v7
	v_cvt_pk_fp8_f32 v9, v4, v10
	v_max_f32_e32 v13, 0, v13
	v_mul_f32_e32 v3, v13, v13
	v_min_f32_e32 v3, 0x43e00000, v3
	v_cvt_pk_fp8_f32 v8, v12, v14 op_sel:[0,0,1]
	v_cvt_pk_fp8_f32 v9, v11, v3 op_sel:[0,0,1]
	v_pk_mul_f32 v[12:13], v[86:87], v[2:3] op_sel_hi:[1,0]
	v_pk_mul_f32 v[14:15], v[84:85], v[2:3] op_sel_hi:[1,0]
	v_pk_mul_f32 v[16:17], v[82:83], v[2:3] op_sel_hi:[1,0]
	v_pk_mul_f32 v[2:3], v[80:81], v[2:3] op_sel_hi:[1,0]
	v_max_f32_e32 v4, 0, v14
	v_max_f32_e32 v2, 0, v2
	v_mul_f32_e32 v2, v2, v2
	v_min_f32_e32 v7, 0x43e00000, v2
	v_max_f32_e32 v2, 0, v15
	v_max_f32_e32 v3, 0, v3
	v_mul_f32_e32 v2, v2, v2
	v_min_f32_e32 v14, 0x43e00000, v2
	v_mul_f32_e32 v2, v3, v3
	v_min_f32_e32 v15, 0x43e00000, v2
	v_max_f32_e32 v2, 0, v12
	v_max_f32_e32 v3, 0, v16
	v_mul_f32_e32 v2, v2, v2
	v_min_f32_e32 v12, 0x43e00000, v2
	v_mul_f32_e32 v2, v3, v3
	v_min_f32_e32 v16, 0x43e00000, v2
	v_max_f32_e32 v2, 0, v13
	v_mov_b32_e32 v3, 0
	v_mul_f32_e32 v4, v4, v4
	v_mul_f32_e32 v2, v2, v2
	v_cvt_pk_fp8_f32 v3, v7, v15
	v_min_f32_e32 v4, 0x43e00000, v4
	v_max_f32_e32 v13, 0, v17
	v_min_f32_e32 v17, 0x43e00000, v2
	v_mov_b32_e32 v2, 0
	v_cvt_pk_fp8_f32 v2, v4, v14
	v_mul_f32_e32 v4, v13, v13
	v_min_f32_e32 v4, 0x43e00000, v4
	v_cvt_pk_fp8_f32 v3, v16, v4 op_sel:[0,0,1]
	v_fmamk_f32 v4, v179, 0x3a000000, v190
	v_rsq_f32_e32 v4, v4
	v_cvt_pk_fp8_f32 v2, v12, v17 op_sel:[0,0,1]
	v_add_co_u32_e32 v12, vcc, s61, v0
	v_lshl_add_u64 v[10:11], v[0:1], 0, s[12:13]
	s_nop 0
	v_addc_co_u32_e32 v13, vcc, 0, v1, vcc
	global_store_dwordx2 v[12:13], v[8:9], off
	global_store_dwordx2 v[10:11], v[2:3], off offset:128
	v_mul_f32_e32 v2, 0x3d000000, v4
	v_pk_mul_f32 v[8:9], v[78:79], v[2:3] op_sel_hi:[1,0]
	v_pk_mul_f32 v[10:11], v[76:77], v[2:3] op_sel_hi:[1,0]
	v_pk_mul_f32 v[12:13], v[74:75], v[2:3] op_sel_hi:[1,0]
	v_max_f32_e32 v8, 0, v8
	v_max_f32_e32 v7, 0, v11
	v_max_f32_e32 v11, 0, v12
	v_mul_f32_e32 v8, v8, v8
	v_pk_mul_f32 v[14:15], v[72:73], v[2:3] op_sel_hi:[1,0]
	v_min_f32_e32 v12, 0x43e00000, v8
	v_mul_f32_e32 v8, v11, v11
	v_max_f32_e32 v3, 0, v10
	v_max_f32_e32 v4, 0, v14
	v_max_f32_e32 v10, 0, v15
	v_min_f32_e32 v11, 0x43e00000, v8
	v_max_f32_e32 v8, 0, v9
	v_mul_f32_e32 v3, v3, v3
	v_mul_f32_e32 v4, v4, v4
	v_mul_f32_e32 v7, v7, v7
	v_mul_f32_e32 v10, v10, v10
	v_mul_f32_e32 v8, v8, v8
	v_min_f32_e32 v3, 0x43e00000, v3
	v_min_f32_e32 v4, 0x43e00000, v4
	v_min_f32_e32 v7, 0x43e00000, v7
	v_min_f32_e32 v10, 0x43e00000, v10
	v_min_f32_e32 v14, 0x43e00000, v8
	v_mov_b32_e32 v8, 0
	v_mov_b32_e32 v9, 0
	v_cvt_pk_fp8_f32 v8, v3, v7
	v_cvt_pk_fp8_f32 v9, v4, v10
	v_max_f32_e32 v13, 0, v13
	v_mul_f32_e32 v3, v13, v13
	v_min_f32_e32 v3, 0x43e00000, v3
	v_cvt_pk_fp8_f32 v8, v12, v14 op_sel:[0,0,1]
	v_cvt_pk_fp8_f32 v9, v11, v3 op_sel:[0,0,1]
	v_pk_mul_f32 v[12:13], v[70:71], v[2:3] op_sel_hi:[1,0]
	v_pk_mul_f32 v[14:15], v[68:69], v[2:3] op_sel_hi:[1,0]
	v_pk_mul_f32 v[16:17], v[66:67], v[2:3] op_sel_hi:[1,0]
	v_pk_mul_f32 v[2:3], v[64:65], v[2:3] op_sel_hi:[1,0]
	v_max_f32_e32 v4, 0, v14
	v_max_f32_e32 v2, 0, v2
	v_mul_f32_e32 v2, v2, v2
	v_min_f32_e32 v7, 0x43e00000, v2
	v_max_f32_e32 v2, 0, v15
	v_max_f32_e32 v3, 0, v3
	v_mul_f32_e32 v2, v2, v2
	v_min_f32_e32 v14, 0x43e00000, v2
	v_mul_f32_e32 v2, v3, v3
	v_min_f32_e32 v15, 0x43e00000, v2
	v_max_f32_e32 v2, 0, v12
	v_max_f32_e32 v3, 0, v16
	v_mul_f32_e32 v2, v2, v2
	v_min_f32_e32 v12, 0x43e00000, v2
	v_mul_f32_e32 v2, v3, v3
	v_min_f32_e32 v16, 0x43e00000, v2
	v_max_f32_e32 v2, 0, v13
	v_mov_b32_e32 v3, 0
	v_mul_f32_e32 v4, v4, v4
	v_mul_f32_e32 v2, v2, v2
	v_cvt_pk_fp8_f32 v3, v7, v15
	v_min_f32_e32 v4, 0x43e00000, v4
	v_max_f32_e32 v13, 0, v17
	v_min_f32_e32 v17, 0x43e00000, v2
	v_mov_b32_e32 v2, 0
	v_cvt_pk_fp8_f32 v2, v4, v14
	v_mul_f32_e32 v4, v13, v13
	v_min_f32_e32 v4, 0x43e00000, v4
	v_cvt_pk_fp8_f32 v3, v16, v4 op_sel:[0,0,1]
	v_fmamk_f32 v4, v6, 0x3a000000, v190
	v_rsq_f32_e32 v4, v4
	v_cvt_pk_fp8_f32 v2, v12, v17 op_sel:[0,0,1]
	v_add_co_u32_e32 v6, vcc, s62, v0
	v_lshl_add_u64 v[10:11], v[0:1], 0, s[14:15]
	s_nop 0
	v_addc_co_u32_e32 v7, vcc, 0, v1, vcc
	global_store_dwordx2 v[6:7], v[8:9], off
	global_store_dwordx2 v[10:11], v[2:3], off offset:128
	v_mul_f32_e32 v2, 0x3d000000, v4
	v_pk_mul_f32 v[6:7], v[62:63], v[2:3] op_sel_hi:[1,0]
	v_pk_mul_f32 v[10:11], v[58:59], v[2:3] op_sel_hi:[1,0]
	v_max_f32_e32 v6, 0, v6
	v_pk_mul_f32 v[12:13], v[56:57], v[2:3] op_sel_hi:[1,0]
	v_max_f32_e32 v10, 0, v10
	v_mul_f32_e32 v6, v6, v6
	v_pk_mul_f32 v[8:9], v[60:61], v[2:3] op_sel_hi:[1,0]
	v_max_f32_e32 v4, 0, v12
	v_min_f32_e32 v12, 0x43e00000, v6
; #define PG8_WAIT_V(n) asm volatile("s_waitcnt vmcnt(" #n ")" ::: "memory")
; #define PG8_BAR __builtin_amdgcn_s_barrier()
; template <class Epi, class Sched, bool ALIGN_EPI = false, bool SP2 = false, bool FP8 = false>
; __device__ __forceinline__ void gemm_phase(PG8_LAS unsigned char* lds, const Gemm g, const Sched& S, const Epi& E, int wave_id) {
;     ...
;         if (!has_next) break;
; #pragma unroll
;         for (int a = 0; a < 2; ++a)
; #pragma unroll
;             for (int b = 0; b < 2; ++b)
; #pragma unroll
;                 for (int m = 0; m < 4; ++m)
; #pragma unroll
;                     for (int n = 0; n < 2; ++n) acc[a][b][m][n] = (f32x4){0.f, 0.f, 0.f, 0.f};
;         cur = nxt; cA = nA; cB = nB; ++ui;
;         if constexpr (ALIGN_EPI) { if (wr == 1) PG8_BAR; }
;     }
;     PG8_WAIT_V(0);
;     if constexpr (!ALIGN_EPI) { if (wr == 0) PG8_BAR; }
;     __device__ __forceinline__ void operator()(const f32x4 (&acc)[2][2][4][2], const Unit& u, int wr, int wc, int fr, int fq) const {
;     ...
;         for (int ai = 0; ai < 2; ++ai)
; #pragma unroll
;             for (int m = 0; m < 4; ++m) {
;                 const int row = row0 + ai * HALF + m * 16;
;                 const float rstd = __builtin_amdgcn_rsqf(rs[ai][m] * (1.f / DM) + EPS) * (1.f / W1_SCALE);
; #pragma unroll
;                 for (int bj = 0; bj < 2; ++bj) {
;                     f32x4 v0 = acc[ai][bj][m][0] * rstd, v1 = acc[ai][bj][m][1] * rstd;
; #pragma unroll
;                     for (int e = 0; e < 4; ++e) { const float a = fmaxf(v0[e], 0.f), b = fmaxf(v1[e], 0.f); v0[e] = fminf(a * a, 448.f); v1[e] = fminf(b * b, 448.f); }
;                     int w0 = __builtin_amdgcn_cvt_pk_fp8_f32(v0[0], v0[1], 0, false); w0 = __builtin_amdgcn_cvt_pk_fp8_f32(v0[2], v0[3], w0, true);
;                     int w1 = __builtin_amdgcn_cvt_pk_fp8_f32(v1[0], v1[1], 0, false); w1 = __builtin_amdgcn_cvt_pk_fp8_f32(v1[2], v1[3], w1, true);
;                     *(v2u*)(O + (size_t)row * FF + col0 + bj * HALF) = (v2u){(unsigned)w0, (unsigned)w1};
	v_mul_f32_e32 v6, v10, v10
	v_max_f32_e32 v3, 0, v8
	v_max_f32_e32 v8, 0, v9
	v_max_f32_e32 v9, 0, v13
	v_min_f32_e32 v10, 0x43e00000, v6
	v_max_f32_e32 v6, 0, v7
	v_mul_f32_e32 v3, v3, v3
	v_mul_f32_e32 v4, v4, v4
	v_mul_f32_e32 v8, v8, v8
	v_mul_f32_e32 v9, v9, v9
	v_mul_f32_e32 v6, v6, v6
	v_min_f32_e32 v3, 0x43e00000, v3
	v_min_f32_e32 v4, 0x43e00000, v4
	v_min_f32_e32 v8, 0x43e00000, v8
	v_min_f32_e32 v9, 0x43e00000, v9
	v_min_f32_e32 v13, 0x43e00000, v6
	v_mov_b32_e32 v6, 0
	v_mov_b32_e32 v7, 0
	v_cvt_pk_fp8_f32 v6, v3, v8
	v_cvt_pk_fp8_f32 v7, v4, v9
	v_max_f32_e32 v11, 0, v11
	v_mul_f32_e32 v3, v11, v11
	v_min_f32_e32 v3, 0x43e00000, v3
	v_cvt_pk_fp8_f32 v6, v12, v13 op_sel:[0,0,1]
	v_cvt_pk_fp8_f32 v7, v10, v3 op_sel:[0,0,1]
	v_pk_mul_f32 v[10:11], v[54:55], v[2:3] op_sel_hi:[1,0]
	v_pk_mul_f32 v[12:13], v[52:53], v[2:3] op_sel_hi:[1,0]
	v_pk_mul_f32 v[14:15], v[50:51], v[2:3] op_sel_hi:[1,0]
	v_pk_mul_f32 v[2:3], v[48:49], v[2:3] op_sel_hi:[1,0]
	v_max_f32_e32 v4, 0, v12
	v_max_f32_e32 v2, 0, v2
	v_mul_f32_e32 v2, v2, v2
	v_min_f32_e32 v12, 0x43e00000, v2
	v_max_f32_e32 v2, 0, v13
	v_max_f32_e32 v3, 0, v3
	v_mul_f32_e32 v2, v2, v2
	v_min_f32_e32 v13, 0x43e00000, v2
	v_mul_f32_e32 v2, v3, v3
	v_min_f32_e32 v16, 0x43e00000, v2
	v_max_f32_e32 v2, 0, v10
	v_max_f32_e32 v3, 0, v14
	v_mul_f32_e32 v2, v2, v2
	v_min_f32_e32 v10, 0x43e00000, v2
	v_mul_f32_e32 v2, v3, v3
	v_min_f32_e32 v14, 0x43e00000, v2
	v_max_f32_e32 v2, 0, v11
	v_mul_f32_e32 v4, v4, v4
	v_mul_f32_e32 v2, v2, v2
	v_mov_b32_e32 v3, 0
	v_min_f32_e32 v4, 0x43e00000, v4
	v_max_f32_e32 v11, 0, v15
	v_min_f32_e32 v15, 0x43e00000, v2
	v_mov_b32_e32 v2, 0
	v_cvt_pk_fp8_f32 v3, v12, v16
	v_cvt_pk_fp8_f32 v2, v4, v13
	v_mul_f32_e32 v4, v11, v11
	v_min_f32_e32 v4, 0x43e00000, v4
	v_cvt_pk_fp8_f32 v3, v14, v4 op_sel:[0,0,1]
	v_fmamk_f32 v4, v5, 0x3a000000, v190
	v_cvt_pk_fp8_f32 v2, v10, v15 op_sel:[0,0,1]
	v_rsq_f32_e32 v10, v4
	v_add_co_u32_e32 v4, vcc, s63, v0
	v_lshl_add_u64 v[8:9], v[0:1], 0, s[16:17]
	s_nop 0
	v_addc_co_u32_e32 v5, vcc, 0, v1, vcc
	global_store_dwordx2 v[4:5], v[6:7], off
	global_store_dwordx2 v[8:9], v[2:3], off offset:128
	v_mul_f32_e32 v2, 0x3d000000, v10
	v_pk_mul_f32 v[4:5], v[46:47], v[2:3] op_sel_hi:[1,0]
	v_pk_mul_f32 v[8:9], v[42:43], v[2:3] op_sel_hi:[1,0]
	v_max_f32_e32 v4, 0, v4
	v_pk_mul_f32 v[6:7], v[44:45], v[2:3] op_sel_hi:[1,0]
	v_pk_mul_f32 v[10:11], v[40:41], v[2:3] op_sel_hi:[1,0]
	v_max_f32_e32 v8, 0, v8
	v_mul_f32_e32 v4, v4, v4
	v_max_f32_e32 v3, 0, v6
	v_max_f32_e32 v6, 0, v10
	v_max_f32_e32 v10, 0, v11
	v_min_f32_e32 v11, 0x43e00000, v4
	v_mul_f32_e32 v4, v8, v8
	v_max_f32_e32 v7, 0, v7
	v_min_f32_e32 v8, 0x43e00000, v4
	v_max_f32_e32 v4, 0, v5
	v_mul_f32_e32 v3, v3, v3
	v_mul_f32_e32 v6, v6, v6
	v_mul_f32_e32 v7, v7, v7
	v_mul_f32_e32 v10, v10, v10
	v_mul_f32_e32 v4, v4, v4
	v_min_f32_e32 v3, 0x43e00000, v3
	v_min_f32_e32 v6, 0x43e00000, v6
	v_min_f32_e32 v7, 0x43e00000, v7
	v_min_f32_e32 v10, 0x43e00000, v10
	v_min_f32_e32 v12, 0x43e00000, v4
	v_mov_b32_e32 v4, 0
	v_mov_b32_e32 v5, 0
	v_cvt_pk_fp8_f32 v4, v3, v7
	v_cvt_pk_fp8_f32 v5, v6, v10
	v_max_f32_e32 v9, 0, v9
	v_mul_f32_e32 v3, v9, v9
	v_min_f32_e32 v3, 0x43e00000, v3
	v_cvt_pk_fp8_f32 v4, v11, v12 op_sel:[0,0,1]
	v_cvt_pk_fp8_f32 v5, v8, v3 op_sel:[0,0,1]
	v_pk_mul_f32 v[8:9], v[38:39], v[2:3] op_sel_hi:[1,0]
	v_pk_mul_f32 v[10:11], v[36:37], v[2:3] op_sel_hi:[1,0]
	v_pk_mul_f32 v[12:13], v[34:35], v[2:3] op_sel_hi:[1,0]
	v_pk_mul_f32 v[2:3], v[32:33], v[2:3] op_sel_hi:[1,0]
	v_max_f32_e32 v10, 0, v10
	v_max_f32_e32 v2, 0, v2
	v_mul_f32_e32 v2, v2, v2
	v_min_f32_e32 v14, 0x43e00000, v2
	v_max_f32_e32 v2, 0, v11
	v_max_f32_e32 v3, 0, v3
	v_mul_f32_e32 v2, v2, v2
	v_min_f32_e32 v11, 0x43e00000, v2
	v_mul_f32_e32 v2, v3, v3
	v_min_f32_e32 v15, 0x43e00000, v2
	v_max_f32_e32 v2, 0, v8
	v_max_f32_e32 v3, 0, v12
	v_mul_f32_e32 v2, v2, v2
	v_min_f32_e32 v8, 0x43e00000, v2
	v_mul_f32_e32 v2, v3, v3
	v_min_f32_e32 v12, 0x43e00000, v2
	v_max_f32_e32 v2, 0, v9
	v_mul_f32_e32 v10, v10, v10
	v_mul_f32_e32 v2, v2, v2
	v_min_f32_e32 v10, 0x43e00000, v10
	v_max_f32_e32 v9, 0, v13
	v_min_f32_e32 v13, 0x43e00000, v2
	v_mov_b32_e32 v2, 0
	v_mov_b32_e32 v3, 0
	v_cvt_pk_fp8_f32 v2, v10, v11
	v_cvt_pk_fp8_f32 v3, v14, v15
	v_mul_f32_e32 v9, v9, v9
	v_min_f32_e32 v9, 0x43e00000, v9
	v_lshl_add_u64 v[6:7], v[0:1], 0, s[18:19]
	v_cvt_pk_fp8_f32 v2, v8, v13 op_sel:[0,0,1]
	v_cvt_pk_fp8_f32 v3, v12, v9 op_sel:[0,0,1]
	v_add_co_u32_e32 v0, vcc, s64, v0
	s_nop 1
	v_addc_co_u32_e32 v1, vcc, 0, v1, vcc
	s_and_b64 vcc, exec, s[0:1]
	global_store_dwordx2 v[0:1], v[4:5], off
	global_store_dwordx2 v[6:7], v[2:3], off offset:128
	s_cbranch_vccz .LBB0_412
	s_waitcnt vmcnt(0)
	s_cmpk_gt_u32 s42, 0xff
	s_cbranch_scc1 .LBB0_423
	s_barrier

; #define PG8_STAGE(bufoff, gbase, voff) do { _Pragma("unroll") for (int _i = 0; _i < 2; ++_i) \
;         __builtin_amdgcn_global_load_lds((const unsigned*)((const char*)(gbase) + (voff)[_i]), (PG8_LAS unsigned*)(lds + (bufoff) + ldsw + _i * 8192), 16, 0, 0); } while (0)
; #define PG8_LDA(dst, b, h) do { _Pragma("unroll") for (int m = 0; m < 4; ++m) { if constexpr (FP8) dst##8[m] = PG8_LD32(lds + PG8_SA(b, h) + aoff + m * 2048); else { _Pragma("unroll") for (int k = 0; k < 2; ++k) dst[m][k] = *(const PG8_LAS bf16x8*)(lds + PG8_SA(b, h) + aoff + m * 2048 + k * 1024); } } } while (0)
; #define PG8_LDB(dst, b, h) do { _Pragma("unroll") for (int n = 0; n < 2; ++n) { if constexpr (FP8) dst##8[n] = PG8_LD32(lds + PG8_SB(b, h) + boff + n * 2048); else { _Pragma("unroll") for (int k = 0; k < 2; ++k) dst[n][k] = *(const PG8_LAS bf16x8*)(lds + PG8_SB(b, h) + boff + n * 2048 + k * 1024); } } } while (0)
; #define PG8_WAIT_V(n) asm volatile("s_waitcnt vmcnt(" #n ")" ::: "memory")
; #define PG8_WAIT_L(n) asm volatile("s_waitcnt lgkmcnt(" #n ")" ::: "memory")
; #define PG8_BAR __builtin_amdgcn_s_barrier()
; #define PG8_SCHED __builtin_amdgcn_sched_barrier(0)
; template <class Epi, class Sched, bool ALIGN_EPI = false, bool SP2 = false, bool FP8 = false>
; __device__ __forceinline__ void gemm_phase(PG8_LAS unsigned char* lds, const Gemm g, const Sched& S, const Epi& E, int wave_id) {
;     ...
;             PG8_LDB(B0, 0, 0); PG8_LDB(B1, 0, 1); PG8_SCHED; PG8_LDA(At, 0, 0); PG8_STAGE(PG8_SA(1, 1), a1 + hstep, voffA);
;             PG8_WAIT_V(8); PG8_WAIT_L(0); PG8_BAR; PG8_MMA(0, 0, At, B0); PG8_MMA(0, 1, At, B1); PG8_BAR; PG8_SCHED;
;             PG8_LDA(At, 0, 1); PG8_STAGE(PG8_SB(0, 0), b2, voffB); PG8_STAGE(PG8_SB(0, 1), b2 + hstep, voffB); PG8_STAGE(PG8_SA(0, 0), a2, voffA);
;             PG8_WAIT_V(8); PG8_WAIT_L(0); PG8_BAR; PG8_MMA(1, 0, At, B0); PG8_MMA(1, 1, At, B1); PG8_BAR; PG8_SCHED;
;             PG8_LDB(B0, 1, 0); PG8_LDB(B1, 1, 1); PG8_SCHED; PG8_LDA(At, 1, 0); PG8_STAGE(PG8_SA(0, 1), a2 + hstep, voffA);
;             PG8_WAIT_V(8); PG8_WAIT_L(0); PG8_BAR; PG8_MMA(0, 0, At, B0); PG8_MMA(0, 1, At, B1); PG8_BAR; PG8_SCHED;
.LBB0_497:
	ds_read_b128 v[16:19], v191
	ds_read_b128 v[20:23], v191 offset:1024
	ds_read_b128 v[24:27], v191 offset:2048
	ds_read_b128 v[28:31], v191 offset:3072
	s_waitcnt lgkmcnt(0)
	ds_read_b128 v[0:3], v192
	ds_read_b128 v[4:7], v192 offset:1024
	ds_read_b128 v[8:11], v192 offset:2048
	ds_read_b128 v[12:15], v192 offset:3072
	s_add_u32 s28, s26, 0xfff00080
	s_addc_u32 s29, s27, -1
	s_cmp_eq_u32 s58, 60
	s_cselect_b32 s31, s17, s29
	s_cselect_b32 s30, s23, s28
	s_cselect_b32 s29, s15, s57
	s_cselect_b32 s28, s55, s56
	v_lshl_add_u64 v[184:185], s[26:27], 0, v[168:169]
	s_add_i32 m0, s25, 0xc000
	ds_read_b128 v[176:179], v193
	ds_read_b128 v[180:183], v193 offset:1024
	ds_read_b128 v[194:197], v193 offset:2048
	ds_read_b128 v[198:201], v193 offset:3072
	ds_read_b128 v[202:205], v193 offset:4096
	ds_read_b128 v[206:209], v193 offset:5120
	ds_read_b128 v[210:213], v193 offset:6144
	ds_read_b128 v[214:217], v193 offset:7168
	global_load_lds_dwordx4 v[184:185], off
	v_lshl_add_u64 v[184:185], s[26:27], 0, v[170:171]
	s_add_i32 m0, s25, 0xe000
	s_nop 0
	global_load_lds_dwordx4 v[184:185], off
	s_waitcnt vmcnt(8)
	s_waitcnt lgkmcnt(0)
	s_barrier
	s_waitcnt lgkmcnt(0)
	v_mfma_f32_16x16x128_f8f6f4 v[156:159], v[16:23], v[176:183], v[156:159]
	v_mfma_f32_16x16x128_f8f6f4 v[152:155], v[24:31], v[176:183], v[152:155]
	v_mfma_f32_16x16x128_f8f6f4 v[140:143], v[16:23], v[194:201], v[140:143]
	v_mfma_f32_16x16x128_f8f6f4 v[136:139], v[24:31], v[194:201], v[136:139]
	v_mfma_f32_16x16x128_f8f6f4 v[124:127], v[16:23], v[202:209], v[124:127]
	v_mfma_f32_16x16x128_f8f6f4 v[120:123], v[24:31], v[202:209], v[120:123]
	v_mfma_f32_16x16x128_f8f6f4 v[108:111], v[16:23], v[210:217], v[108:111]
	v_mfma_f32_16x16x128_f8f6f4 v[104:107], v[24:31], v[210:217], v[104:107]
	v_mfma_f32_16x16x128_f8f6f4 v[148:151], v[0:7], v[176:183], v[148:151]
	v_mfma_f32_16x16x128_f8f6f4 v[144:147], v[8:15], v[176:183], v[144:147]
	v_mfma_f32_16x16x128_f8f6f4 v[132:135], v[0:7], v[194:201], v[132:135]
	v_mfma_f32_16x16x128_f8f6f4 v[128:131], v[8:15], v[194:201], v[128:131]
	v_mfma_f32_16x16x128_f8f6f4 v[116:119], v[0:7], v[202:209], v[116:119]
	v_mfma_f32_16x16x128_f8f6f4 v[112:115], v[8:15], v[202:209], v[112:115]
	v_mfma_f32_16x16x128_f8f6f4 v[100:103], v[0:7], v[210:217], v[100:103]
	v_mfma_f32_16x16x128_f8f6f4 v[96:99], v[8:15], v[210:217], v[96:99]
	s_barrier
	s_add_i32 s59, s53, s13
	v_lshl_add_u64 v[176:177], s[28:29], 0, v[162:163]
	s_mov_b32 m0, s59
	ds_read_b128 v[194:197], v193 offset:16384
	ds_read_b128 v[198:201], v193 offset:17408
	ds_read_b128 v[202:205], v193 offset:18432
	ds_read_b128 v[206:209], v193 offset:19456
	ds_read_b128 v[210:213], v193 offset:20480
	ds_read_b128 v[214:217], v193 offset:21504
	ds_read_b128 v[218:221], v193 offset:22528
	ds_read_b128 v[222:225], v193 offset:23552
	global_load_lds_dwordx4 v[176:177], off
	s_add_i32 m0, s59, 0x2000
	s_add_u32 s60, s28, 0x100000
	v_lshl_add_u64 v[178:179], s[28:29], 0, v[166:167]
	s_addc_u32 s61, s29, 0
	s_add_i32 s59, s54, s13
	global_load_lds_dwordx4 v[178:179], off
	v_lshl_add_u64 v[180:181], s[60:61], 0, v[162:163]
	s_mov_b32 m0, s59
	v_lshl_add_u64 v[182:183], s[30:31], 0, v[164:165]
	global_load_lds_dwordx4 v[180:181], off
	v_lshl_add_u64 v[180:181], s[60:61], 0, v[166:167]
	s_add_i32 m0, s59, 0x2000
	s_nop 0
	global_load_lds_dwordx4 v[180:181], off
	v_lshl_add_u64 v[180:181], s[30:31], 0, v[160:161]
	s_mov_b32 m0, s25
	s_nop 0
	global_load_lds_dwordx4 v[180:181], off
	s_mov_b32 m0, s34
	s_nop 0
	global_load_lds_dwordx4 v[182:183], off
	s_waitcnt vmcnt(8)
	s_waitcnt lgkmcnt(0)
	s_barrier
	s_waitcnt lgkmcnt(0)
	v_mfma_f32_16x16x128_f8f6f4 v[92:95], v[16:23], v[194:201], v[92:95]
	v_mfma_f32_16x16x128_f8f6f4 v[88:91], v[24:31], v[194:201], v[88:91]
	v_mfma_f32_16x16x128_f8f6f4 v[76:79], v[16:23], v[202:209], v[76:79]
	v_mfma_f32_16x16x128_f8f6f4 v[72:75], v[24:31], v[202:209], v[72:75]
	v_mfma_f32_16x16x128_f8f6f4 v[60:63], v[16:23], v[210:217], v[60:63]
	v_mfma_f32_16x16x128_f8f6f4 v[56:59], v[24:31], v[210:217], v[56:59]
	v_mfma_f32_16x16x128_f8f6f4 v[44:47], v[16:23], v[218:225], v[44:47]
	v_mfma_f32_16x16x128_f8f6f4 v[40:43], v[24:31], v[218:225], v[40:43]
	v_mfma_f32_16x16x128_f8f6f4 v[84:87], v[0:7], v[194:201], v[84:87]
	v_mfma_f32_16x16x128_f8f6f4 v[80:83], v[8:15], v[194:201], v[80:83]
	v_mfma_f32_16x16x128_f8f6f4 v[68:71], v[0:7], v[202:209], v[68:71]
	v_mfma_f32_16x16x128_f8f6f4 v[64:67], v[8:15], v[202:209], v[64:67]
	v_mfma_f32_16x16x128_f8f6f4 v[52:55], v[0:7], v[210:217], v[52:55]
	v_mfma_f32_16x16x128_f8f6f4 v[48:51], v[8:15], v[210:217], v[48:51]
	v_mfma_f32_16x16x128_f8f6f4 v[36:39], v[0:7], v[218:225], v[36:39]
	v_mfma_f32_16x16x128_f8f6f4 v[32:35], v[8:15], v[218:225], v[32:35]
	s_barrier
	s_add_i32 s59, 0, 0x18000
	s_add_i32 s60, 0, 0x1c000
	v_add_u32_e32 v12, s59, v187
	v_add_u32_e32 v28, s60, v187
	ds_read_b128 v[0:3], v12
	ds_read_b128 v[4:7], v12 offset:1024
	ds_read_b128 v[8:11], v12 offset:2048
	ds_read_b128 v[12:15], v12 offset:3072
	ds_read_b128 v[16:19], v28
	ds_read_b128 v[20:23], v28 offset:1024
	ds_read_b128 v[24:27], v28 offset:2048
	ds_read_b128 v[28:31], v28 offset:3072
	s_add_u32 s30, s30, 0x100000
	s_addc_u32 s31, s31, 0
	s_mov_b32 m0, s35
	v_lshl_add_u64 v[184:185], s[30:31], 0, v[160:161]
	ds_read_b128 v[194:197], v193 offset:32768
	ds_read_b128 v[198:201], v193 offset:33792
	ds_read_b128 v[202:205], v193 offset:34816
	ds_read_b128 v[206:209], v193 offset:35840
	ds_read_b128 v[210:213], v193 offset:36864
	ds_read_b128 v[214:217], v193 offset:37888
	ds_read_b128 v[218:221], v193 offset:38912
	ds_read_b128 v[222:225], v193 offset:39936
	global_load_lds_dwordx4 v[184:185], off
	v_lshl_add_u64 v[184:185], s[30:31], 0, v[164:165]
	s_mov_b32 m0, s36
	s_nop 0
	global_load_lds_dwordx4 v[184:185], off
	s_waitcnt vmcnt(8)
	s_waitcnt lgkmcnt(0)
	s_barrier
; #define PG8_STAGE(bufoff, gbase, voff) do { _Pragma("unroll") for (int _i = 0; _i < 2; ++_i) \
;         __builtin_amdgcn_global_load_lds((const unsigned*)((const char*)(gbase) + (voff)[_i]), (PG8_LAS unsigned*)(lds + (bufoff) + ldsw + _i * 8192), 16, 0, 0); } while (0)
; #define PG8_LDA(dst, b, h) do { _Pragma("unroll") for (int m = 0; m < 4; ++m) { if constexpr (FP8) dst##8[m] = PG8_LD32(lds + PG8_SA(b, h) + aoff + m * 2048); else { _Pragma("unroll") for (int k = 0; k < 2; ++k) dst[m][k] = *(const PG8_LAS bf16x8*)(lds + PG8_SA(b, h) + aoff + m * 2048 + k * 1024); } } } while (0)
; #define PG8_WAIT_V(n) asm volatile("s_waitcnt vmcnt(" #n ")" ::: "memory")
; #define PG8_WAIT_L(n) asm volatile("s_waitcnt lgkmcnt(" #n ")" ::: "memory")
; #define PG8_BAR __builtin_amdgcn_s_barrier()
; #define PG8_SCHED __builtin_amdgcn_sched_barrier(0)
; template <class Epi, class Sched, bool ALIGN_EPI = false, bool SP2 = false, bool FP8 = false>
; __device__ __forceinline__ void gemm_phase(PG8_LAS unsigned char* lds, const Gemm g, const Sched& S, const Epi& E, int wave_id) {
;     ...
;             PG8_WAIT_V(8); PG8_WAIT_L(0); PG8_BAR; PG8_MMA(0, 0, At, B0); PG8_MMA(0, 1, At, B1); PG8_BAR; PG8_SCHED;
;             PG8_LDA(At, 1, 1); PG8_STAGE(PG8_SB(1, 0), b3, voffB); PG8_STAGE(PG8_SB(1, 1), b3 + hstep, voffB); PG8_STAGE(PG8_SA(1, 0), a3, voffA);
;             PG8_WAIT_V(8); PG8_WAIT_L(0); PG8_BAR; PG8_MMA(1, 0, At, B0); PG8_MMA(1, 1, At, B1); PG8_BAR; PG8_SCHED;
	s_waitcnt lgkmcnt(0)
	v_mfma_f32_16x16x128_f8f6f4 v[156:159], v[0:7], v[194:201], v[156:159]
	v_mfma_f32_16x16x128_f8f6f4 v[152:155], v[8:15], v[194:201], v[152:155]
	v_mfma_f32_16x16x128_f8f6f4 v[140:143], v[0:7], v[202:209], v[140:143]
	v_mfma_f32_16x16x128_f8f6f4 v[136:139], v[8:15], v[202:209], v[136:139]
	v_mfma_f32_16x16x128_f8f6f4 v[124:127], v[0:7], v[210:217], v[124:127]
	v_mfma_f32_16x16x128_f8f6f4 v[120:123], v[8:15], v[210:217], v[120:123]
	v_mfma_f32_16x16x128_f8f6f4 v[108:111], v[0:7], v[218:225], v[108:111]
	v_mfma_f32_16x16x128_f8f6f4 v[104:107], v[8:15], v[218:225], v[104:107]
	v_mfma_f32_16x16x128_f8f6f4 v[148:151], v[16:23], v[194:201], v[148:151]
	v_mfma_f32_16x16x128_f8f6f4 v[144:147], v[24:31], v[194:201], v[144:147]
	v_mfma_f32_16x16x128_f8f6f4 v[132:135], v[16:23], v[202:209], v[132:135]
	v_mfma_f32_16x16x128_f8f6f4 v[128:131], v[24:31], v[202:209], v[128:131]
	v_mfma_f32_16x16x128_f8f6f4 v[116:119], v[16:23], v[210:217], v[116:119]
	v_mfma_f32_16x16x128_f8f6f4 v[112:115], v[24:31], v[210:217], v[112:115]
	v_mfma_f32_16x16x128_f8f6f4 v[100:103], v[16:23], v[218:225], v[100:103]
	v_mfma_f32_16x16x128_f8f6f4 v[96:99], v[24:31], v[218:225], v[96:99]
	s_barrier
	s_add_i32 s30, s59, s13
	v_lshl_add_u64 v[176:177], v[176:177], 0, s[10:11]
	s_mov_b32 m0, s30
	ds_read_b128 v[194:197], v193 offset:49152
	ds_read_b128 v[198:201], v193 offset:50176
	ds_read_b128 v[202:205], v193 offset:51200
	ds_read_b128 v[206:209], v193 offset:52224
	ds_read_b128 v[210:213], v193 offset:53248
	ds_read_b128 v[214:217], v193 offset:54272
	ds_read_b128 v[218:221], v193 offset:55296
	ds_read_b128 v[222:225], v193 offset:56320
	global_load_lds_dwordx4 v[176:177], off
	s_add_i32 m0, s30, 0x2000
	s_add_u32 s28, s28, 0x100080
	v_lshl_add_u64 v[176:177], v[178:179], 0, s[10:11]
	s_addc_u32 s29, s29, 0
	s_add_i32 s30, s60, s13
	global_load_lds_dwordx4 v[176:177], off
	v_lshl_add_u64 v[176:177], s[28:29], 0, v[162:163]
	s_mov_b32 m0, s30
	s_nop 0
	global_load_lds_dwordx4 v[176:177], off
	v_lshl_add_u64 v[176:177], s[28:29], 0, v[166:167]
	s_add_i32 m0, s30, 0x2000
	s_nop 0
	global_load_lds_dwordx4 v[176:177], off
	v_lshl_add_u64 v[176:177], v[180:181], 0, s[10:11]
	s_mov_b32 m0, s42
	s_nop 0
	global_load_lds_dwordx4 v[176:177], off
	v_lshl_add_u64 v[176:177], v[182:183], 0, s[10:11]
	s_mov_b32 m0, s43
	s_nop 0
	global_load_lds_dwordx4 v[176:177], off
	s_waitcnt vmcnt(8)
	s_waitcnt lgkmcnt(0)
	s_barrier
	s_waitcnt lgkmcnt(0)
	v_mfma_f32_16x16x128_f8f6f4 v[92:95], v[0:7], v[194:201], v[92:95]
	v_mfma_f32_16x16x128_f8f6f4 v[88:91], v[8:15], v[194:201], v[88:91]
	v_mfma_f32_16x16x128_f8f6f4 v[76:79], v[0:7], v[202:209], v[76:79]
	v_mfma_f32_16x16x128_f8f6f4 v[72:75], v[8:15], v[202:209], v[72:75]
	v_mfma_f32_16x16x128_f8f6f4 v[60:63], v[0:7], v[210:217], v[60:63]
	v_mfma_f32_16x16x128_f8f6f4 v[56:59], v[8:15], v[210:217], v[56:59]
	v_mfma_f32_16x16x128_f8f6f4 v[44:47], v[0:7], v[218:225], v[44:47]
	v_mfma_f32_16x16x128_f8f6f4 v[40:43], v[8:15], v[218:225], v[40:43]
	v_mfma_f32_16x16x128_f8f6f4 v[84:87], v[16:23], v[194:201], v[84:87]
	v_mfma_f32_16x16x128_f8f6f4 v[80:83], v[24:31], v[194:201], v[80:83]
	v_mfma_f32_16x16x128_f8f6f4 v[68:71], v[16:23], v[202:209], v[68:71]
	v_mfma_f32_16x16x128_f8f6f4 v[64:67], v[24:31], v[202:209], v[64:67]
	v_mfma_f32_16x16x128_f8f6f4 v[52:55], v[16:23], v[210:217], v[52:55]
	v_mfma_f32_16x16x128_f8f6f4 v[48:51], v[24:31], v[210:217], v[48:51]
	v_mfma_f32_16x16x128_f8f6f4 v[36:39], v[16:23], v[218:225], v[36:39]
	v_mfma_f32_16x16x128_f8f6f4 v[32:35], v[24:31], v[218:225], v[32:35]
	s_barrier
	s_add_i32 s58, s58, 2
	s_add_u32 s26, s26, 0x100
	s_addc_u32 s27, s27, 0
	s_add_u32 s56, s56, 0x100
	s_addc_u32 s57, s57, 0
	s_cmp_gt_u32 s58, 61
	s_cbranch_scc0 .LBB0_497
;     __device__ __forceinline__ void operator()(const f32x4 (&acc)[2][2][4][2], const Unit& u, int wr, int wc, int fr, int fq) const {
;         const int row0 = u.pm * BM + wr * 64 + fr, col0 = u.pn * BM + wc * 32 + 8 * fq;
; #pragma unroll
;         for (int ai = 0; ai < 2; ++ai) {
;             f32x4 rv[4][2][2];
; #pragma unroll
;             for (int m = 0; m < 4; ++m)
; #pragma unroll
;                 for (int bj = 0; bj < 2; ++bj) {
;                     const size_t off = (size_t)(row0 + ai * HALF + m * 16) * DM + col0 + bj * HALF;
;                     if (RES_BF16) {
;                         const v4u t = *(const v4u*)(Yb + off);
;                         rv[m][bj][0] = (f32x4){__builtin_bit_cast(float, t.x << 16), __builtin_bit_cast(float, t.x & 0xffff0000u), __builtin_bit_cast(float, t.y << 16), __builtin_bit_cast(float, t.y & 0xffff0000u)};
;                         rv[m][bj][1] = (f32x4){__builtin_bit_cast(float, t.z << 16), __builtin_bit_cast(float, t.z & 0xffff0000u), __builtin_bit_cast(float, t.w << 16), __builtin_bit_cast(float, t.w & 0xffff0000u)};
;                     } else { rv[m][bj][0] = *(const f32x4*)(R + off); rv[m][bj][1] = *(const f32x4*)(R + off + 4); }
;                 }
;             asm volatile("" ::: "memory");
; #pragma unroll
;             for (int m = 0; m < 4; ++m) {
;                 const int row = row0 + ai * HALF + m * 16; float s = 0.f;
; #pragma unroll
;                 for (int bj = 0; bj < 2; ++bj) {
;                     const size_t off = (size_t)row * DM + col0 + bj * HALF;
;                     const f32x4 v0 = acc[ai][bj][m][0] * ascale + rv[m][bj][0], v1 = acc[ai][bj][m][1] * ascale + rv[m][bj][1];
;                     { v4u w; w.x = cvt_pk_bf16(v0[0], v0[1]); w.y = cvt_pk_bf16(v0[2], v0[3]); w.z = cvt_pk_bf16(v1[0], v1[1]); w.w = cvt_pk_bf16(v1[2], v1[3]); *(v4u*)(Yb + off) = w; }
;                     if (!RES_BF16) { int w0 = __builtin_amdgcn_cvt_pk_fp8_f32(v0[0], v0[1], 0, false); w0 = __builtin_amdgcn_cvt_pk_fp8_f32(v0[2], v0[3], w0, true);
;                         int w1 = __builtin_amdgcn_cvt_pk_fp8_f32(v1[0], v1[1], 0, false); w1 = __builtin_amdgcn_cvt_pk_fp8_f32(v1[2], v1[3], w1, true);
;                         *(v2u*)(Y8 + off) = (v2u){(unsigned)w0, (unsigned)w1}; }
	v_lshl_or_b32 v24, s24, 8, v190
	v_lshl_add_u32 v28, s22, 8, v186
	v_ashrrev_i32_e32 v25, 31, v24
	v_lshlrev_b64 v[202:203], 1, v[24:25]
	v_ashrrev_i32_e32 v29, 31, v28
	v_lshl_add_u64 v[26:27], s[38:39], 0, v[202:203]
	v_lshlrev_b64 v[204:205], 12, v[28:29]
	s_nop 15
	s_nop 15
	v_lshl_add_u64 v[0:1], v[26:27], 0, v[204:205]
	global_load_dwordx4 v[194:197], v[0:1], off
	global_load_dwordx4 v[198:201], v[0:1], off offset:256
	v_or_b32_e32 v182, 16, v28
	v_or_b32_e32 v178, 32, v28
	v_or_b32_e32 v30, 48, v28
	v_ashrrev_i32_e32 v183, 31, v182
	v_ashrrev_i32_e32 v179, 31, v178
	v_ashrrev_i32_e32 v31, 31, v30
	v_lshlrev_b64 v[184:185], 12, v[182:183]
	v_lshlrev_b64 v[180:181], 12, v[178:179]
	v_lshlrev_b64 v[176:177], 12, v[30:31]
	v_lshl_add_u64 v[0:1], v[26:27], 0, v[184:185]
	v_lshl_add_u64 v[2:3], v[26:27], 0, v[180:181]
	v_lshl_add_u64 v[206:207], v[26:27], 0, v[176:177]
	global_load_dwordx4 v[20:23], v[0:1], off
	global_load_dwordx4 v[16:19], v[0:1], off offset:256
	global_load_dwordx4 v[12:15], v[2:3], off
	global_load_dwordx4 v[8:11], v[2:3], off offset:256
	global_load_dwordx4 v[4:7], v[206:207], off
	s_nop 0
	global_load_dwordx4 v[0:3], v[206:207], off offset:256
	s_waitcnt vmcnt(0)
	v_lshlrev_b32_e32 v206, 16, v194
	v_and_b32_e32 v207, 0xffff0000, v194
	v_lshlrev_b32_e32 v194, 16, v195
	v_and_b32_e32 v195, 0xffff0000, v195
	v_lshlrev_b32_e32 v210, 16, v198
	v_and_b32_e32 v211, 0xffff0000, v198
	v_lshlrev_b32_e32 v198, 16, v199
	v_and_b32_e32 v199, 0xffff0000, v199
	v_lshlrev_b32_e32 v208, 16, v196
	v_and_b32_e32 v209, 0xffff0000, v196
	v_lshlrev_b32_e32 v196, 16, v197
	v_and_b32_e32 v197, 0xffff0000, v197
	v_lshlrev_b32_e32 v212, 16, v200
	v_and_b32_e32 v213, 0xffff0000, v200
	v_pk_fma_f32 v[158:159], v[158:159], s[12:13], v[194:195] op_sel_hi:[1,0,1]
	v_pk_fma_f32 v[156:157], v[156:157], s[12:13], v[206:207] op_sel_hi:[1,0,1]
	v_pk_fma_f32 v[150:151], v[150:151], s[12:13], v[198:199] op_sel_hi:[1,0,1]
	v_pk_fma_f32 v[148:149], v[148:149], s[12:13], v[210:211] op_sel_hi:[1,0,1]
	v_lshlrev_b32_e32 v200, 16, v201
	v_and_b32_e32 v201, 0xffff0000, v201
	v_pk_fma_f32 v[154:155], v[154:155], s[12:13], v[196:197] op_sel_hi:[1,0,1]
	v_pk_fma_f32 v[152:153], v[152:153], s[12:13], v[208:209] op_sel_hi:[1,0,1]
	v_pk_fma_f32 v[196:197], v[144:145], s[12:13], v[212:213] op_sel_hi:[1,0,1]
	v_cvt_pk_bf16_f32 v144, v156, v157
	v_cvt_pk_bf16_f32 v145, v158, v159
	v_mul_f32_e32 v157, v157, v157
	v_mul_f32_e32 v159, v159, v159
	v_mul_f32_e32 v198, v149, v149
	v_mul_f32_e32 v199, v151, v151
	v_pk_fma_f32 v[194:195], v[146:147], s[12:13], v[200:201] op_sel_hi:[1,0,1]
	v_cvt_pk_bf16_f32 v146, v152, v153
	v_cvt_pk_bf16_f32 v147, v154, v155
	v_mul_f32_e32 v153, v153, v153
	v_mul_f32_e32 v155, v155, v155
	v_mul_f32_e32 v200, v197, v197
	v_fmac_f32_e32 v157, v156, v156
	v_fmac_f32_e32 v159, v158, v158
	v_fmac_f32_e32 v198, v148, v148
	v_fmac_f32_e32 v199, v150, v150
	v_mul_f32_e32 v201, v195, v195
	v_fmac_f32_e32 v153, v152, v152
	v_fmac_f32_e32 v155, v154, v154
	v_fmac_f32_e32 v200, v196, v196
	v_add_f32_e32 v152, v157, v159
	v_add_f32_e32 v154, v198, v199
	v_fmac_f32_e32 v201, v194, v194
	v_add_f32_e32 v152, v153, v152
	v_add_f32_e32 v153, v200, v154
	v_add_f32_e32 v152, v155, v152
	v_add_f32_e32 v153, v201, v153
	v_add_f32_e32 v154, v152, v153
	ds_bpermute_b32 v155, v188, v154
	v_lshl_add_u64 v[152:153], s[38:39], 0, v[204:205]
	v_lshl_add_u64 v[152:153], v[152:153], 0, v[202:203]
	global_store_dwordx4 v[152:153], v[144:147], off
	s_waitcnt lgkmcnt(0)
	s_nop 0
	v_add_f32_e32 v144, v154, v155
	ds_bpermute_b32 v145, v189, v144
	v_cvt_pk_bf16_f32 v146, v148, v149
	v_cvt_pk_bf16_f32 v147, v150, v151
	v_cvt_pk_bf16_f32 v148, v196, v197
	v_cvt_pk_bf16_f32 v149, v194, v195
	global_store_dwordx4 v[152:153], v[146:149], off offset:256
	s_and_saveexec_b64 s[22:23], s[0:1]
	s_cbranch_execz .LBB0_500
	v_lshl_add_u64 v[146:147], v[28:29], 2, s[8:9]
	s_waitcnt lgkmcnt(0)
	v_add_f32_e32 v29, v144, v145
	global_atomic_add_f32 v[146:147], v29, off
